# P8 conv rewritten by hand: contiguous 96-row block per workgroup (neighbor rows hit L2) + 2-deep pipelining; P3 pooling rows remapped the same way
# speedup vs baseline: 1.0276x; 1.0048x over previous
.LBB0_513:
	s_or_b64 exec, exec, s[2:3]
	s_mov_b32 s0, 0xc0000
	v_cmp_gt_i32_e32 vcc, s0, v176
	v_readlane_b32 s0, v255, 13
	s_waitcnt lgkmcnt(0)
	s_barrier
	v_lshl_add_u32 v184, s0, 12, v201
	s_and_saveexec_b64 s[2:3], vcc
	v_readlane_b32 s44, v255, 44
	v_readlane_b32 s42, v255, 58
	v_readlane_b32 s45, v255, 45
	v_readlane_b32 s43, v255, 59
	s_cbranch_execz .LBB0_522
	v_readlane_b32 s56, v255, 9
	v_readlane_b32 s57, v255, 13
	v_readlane_b32 s58, v255, 58
	s_nop 3
	s_mul_i32 s59, s57, 0xc00
	s_add_u32 s60, s59, 0xbff
	v_add_u32_e32 v212, s59, v168
	s_cmp_eq_u32 s56, 0x100
	s_cselect_b32 s61, 0x200, s58
	s_cselect_b32 s60, s60, 0xbffff
	s_cselect_b64 vcc, -1, 0
	s_nop 1
	v_cndmask_b32_e32 v212, v176, v212, vcc
	v_readlane_b32 s0, v255, 13
	s_mov_b64 s[6:7], 0
	v_mov_b32_e32 v2, 0x4000
	v_lshl_add_u32 v15, s0, 12, v201
	v_readlane_b32 s0, v255, 9
	v_readlane_b32 s1, v255, 10
	s_lshl_b32 s0, s0, 12
	s_movk_i32 s1, 0x2000
	v_mov_b32_e32 v3, 0x800
	v_mov_b32_e32 v1, 0
	s_mov_b64 s[8:9], 0x1000
	s_movk_i32 s10, 0x1000
	s_mov_b32 s11, 0xffff0000
	s_movk_i32 s12, 0x7fff
	s_mov_b32 s13, s60
	v_mov_b32_e32 v4, v15
	v_mov_b32_e32 v5, v212
.LBB0_515:
	v_ashrrev_i32_e32 v16, 5, v5
	v_cmp_gt_i32_e32 vcc, s1, v16
	v_and_b32_e32 v7, 0x7ff, v16
	v_add_u32_e32 v8, 0xffffe000, v16
	v_cndmask_b32_e32 v26, v2, v3, vcc
	v_ashrrev_i32_e32 v17, 31, v16
	v_and_b32_e32 v6, 0xf8, v4
	v_cndmask_b32_e32 v29, v8, v7, vcc
	v_add_u32_e32 v18, -1, v26
	v_lshlrev_b64 v[22:23], 13, v[16:17]
	v_mov_b32_e32 v21, v1
	v_lshlrev_b32_e32 v0, 1, v6
	v_min_i32_e32 v20, v29, v18
	v_lshl_add_u64 v[22:23], s[44:45], 0, v[22:23]
	v_cmp_lt_u32_e32 vcc, v29, v26
	v_max_i32_e32 v30, 1, v29
	v_lshlrev_b64 v[24:25], 12, v[20:21]
	v_cndmask_b32_e64 v14, 0, 1.0, vcc
	v_cmp_lt_i32_e32 vcc, -1, v29
	v_lshl_add_u64 v[22:23], v[22:23], 0, v[0:1]
	v_add_u32_e32 v5, s61, v5
	v_sub_u32_e32 v16, v16, v29
	v_add_u32_e32 v27, -1, v29
	v_sub_u32_e32 v32, v20, v30
	v_cndmask_b32_e32 v25, 0, v25, vcc
	v_cndmask_b32_e32 v24, 0, v24, vcc
	v_add_co_u32_e32 v30, vcc, s10, v22
	v_mov_b32_e32 v19, v1
	v_lshlrev_b32_e32 v10, 2, v6
	v_cmp_lt_i32_e64 s[4:5], s13, v5
	v_ashrrev_i32_e32 v17, 31, v16
	v_min_i32_e32 v18, v27, v18
	v_addc_co_u32_e32 v31, vcc, 0, v23, vcc
	global_load_dwordx4 v[6:9], v10, s[54:55] offset:16
	s_nop 0
	global_load_dwordx4 v[10:13], v10, s[54:55]
	s_or_b64 s[6:7], s[4:5], s[6:7]
	v_cmp_lt_u32_e64 s[4:5], v27, v26
	v_lshlrev_b64 v[20:21], 13, v[16:17]
	v_lshlrev_b64 v[26:27], 12, v[18:19]
	global_load_dwordx4 v[16:19], v[30:31], off offset:2048
	v_lshl_add_u64 v[20:21], s[44:45], 0, v[20:21]
	v_cndmask_b32_e64 v28, 0, 1.0, s[4:5]
	v_cmp_lt_i32_e64 s[4:5], 0, v29
	v_lshl_add_u64 v[20:21], v[20:21], 0, v[0:1]
	v_lshl_add_u64 v[20:21], v[20:21], 0, s[8:9]
	v_cndmask_b32_e64 v23, 0, v27, s[4:5]
	v_cndmask_b32_e64 v22, 0, v26, s[4:5]
	v_lshl_add_u64 v[22:23], v[22:23], 1, v[20:21]
	v_lshl_add_u64 v[24:25], v[24:25], 1, v[20:21]
	global_load_dwordx4 v[20:23], v[22:23], off
	s_nop 0
	global_load_dwordx4 v[24:27], v[24:25], off
	v_add_u32_e32 v29, 2, v32
	v_cvt_f32_i32_e32 v29, v29
	v_add_u32_e32 v4, s0, v4
	v_div_scale_f32 v0, s[4:5], v29, v29, 1.0
	v_rcp_f32_e32 v33, v0
	v_div_scale_f32 v32, vcc, 1.0, v29, 1.0
	v_fma_f32 v34, -v0, v33, 1.0
	v_fmac_f32_e32 v33, v34, v33
	v_mul_f32_e32 v34, v32, v33
	v_fma_f32 v35, -v0, v34, v32
	v_fmac_f32_e32 v34, v35, v33
	v_fma_f32 v0, -v0, v34, v32
	v_div_fmas_f32 v0, v0, v33, v34
	v_div_fixup_f32 v0, v0, v29, 1.0
	s_waitcnt vmcnt(3)
	v_mov_b32_e32 v32, v10
	v_mov_b32_e32 v33, v12
	v_mov_b32_e32 v12, v11
	v_mov_b32_e32 v10, v6
	v_mov_b32_e32 v11, v8
	v_mov_b32_e32 v8, v7
	s_waitcnt vmcnt(2)
	v_lshlrev_b32_e32 v7, 16, v17
	v_lshlrev_b32_e32 v6, 16, v16
	v_lshlrev_b32_e32 v35, 16, v19
	v_lshlrev_b32_e32 v34, 16, v18
	v_and_b32_e32 v19, 0xffff0000, v19
	v_and_b32_e32 v18, 0xffff0000, v18
	v_and_b32_e32 v17, 0xffff0000, v17
	v_and_b32_e32 v16, 0xffff0000, v16
	v_mul_f32_e32 v29, 0xbfb8aa3b, v6
	v_mul_f32_e32 v37, 0xbfb8aa3b, v7
	v_mul_f32_e32 v39, 0xbfb8aa3b, v34
	v_mul_f32_e32 v40, 0xbfb8aa3b, v18
	v_mul_f32_e32 v41, 0xbfb8aa3b, v35
	v_mul_f32_e32 v42, 0xbfb8aa3b, v19
	v_mul_f32_e32 v36, 0xbfb8aa3b, v16
	v_mul_f32_e32 v38, 0xbfb8aa3b, v17
	v_exp_f32_e32 v44, v29
	v_exp_f32_e32 v46, v37
	v_exp_f32_e32 v48, v39
	v_exp_f32_e32 v49, v40
	v_exp_f32_e32 v50, v41
	v_exp_f32_e32 v51, v42
	v_exp_f32_e32 v45, v36
	v_exp_f32_e32 v47, v38
	s_waitcnt vmcnt(1)
	v_lshlrev_b32_e32 v37, 16, v21
	v_lshlrev_b32_e32 v36, 16, v20
	v_and_b32_e32 v21, 0xffff0000, v21
	v_and_b32_e32 v20, 0xffff0000, v20
	v_lshlrev_b32_e32 v39, 16, v23
	v_lshlrev_b32_e32 v38, 16, v22
	v_and_b32_e32 v23, 0xffff0000, v23
	v_and_b32_e32 v22, 0xffff0000, v22
	s_waitcnt vmcnt(0)
; __global__ void __launch_bounds__(512, 2) fwd_megakernel(Args a) {
;     ...
;         POOL_GROUP(0) POOL_GROUP(1) POOL_GROUP(2) POOL_GROUP(3)
	v_lshlrev_b32_e32 v41, 16, v25
	v_lshlrev_b32_e32 v40, 16, v24
	v_and_b32_e32 v25, 0xffff0000, v25
	v_and_b32_e32 v24, 0xffff0000, v24
	v_lshlrev_b32_e32 v43, 16, v27
	v_lshlrev_b32_e32 v42, 16, v26
	v_and_b32_e32 v27, 0xffff0000, v27
	v_and_b32_e32 v26, 0xffff0000, v26
	v_pk_fma_f32 v[36:37], v[28:29], v[36:37], 0 op_sel_hi:[0,1,0]
	v_pk_fma_f32 v[20:21], v[28:29], v[20:21], 0 op_sel_hi:[0,1,0]
	v_pk_fma_f32 v[38:39], v[28:29], v[38:39], 0 op_sel_hi:[0,1,0]
	v_pk_fma_f32 v[22:23], v[28:29], v[22:23], 0 op_sel_hi:[0,1,0]
	v_pk_fma_f32 v[28:29], v[14:15], v[40:41], v[36:37] op_sel_hi:[0,1,1]
	v_pk_fma_f32 v[20:21], v[14:15], v[24:25], v[20:21] op_sel_hi:[0,1,1]
	v_add_f32_e32 v44, 1.0, v44
	v_add_f32_e32 v46, 1.0, v46
	v_pk_fma_f32 v[36:37], v[14:15], v[42:43], v[38:39] op_sel_hi:[0,1,1]
	v_pk_fma_f32 v[22:23], v[14:15], v[26:27], v[22:23] op_sel_hi:[0,1,1]
	v_add_f32_e32 v14, 1.0, v48
	v_add_f32_e32 v48, 1.0, v49
	v_add_f32_e32 v49, 1.0, v50
	v_add_f32_e32 v50, 1.0, v51
	v_add_f32_e32 v45, 1.0, v45
	v_add_f32_e32 v47, 1.0, v47
	v_rcp_f32_e32 v38, v44
	v_pk_fma_f32 v[28:29], v[0:1], v[28:29], v[40:41] op_sel_hi:[0,1,1] neg_lo:[0,0,1] neg_hi:[0,0,1]
	v_rcp_f32_e32 v39, v46
	v_pk_fma_f32 v[20:21], v[0:1], v[20:21], v[24:25] op_sel_hi:[0,1,1] neg_lo:[0,0,1] neg_hi:[0,0,1]
	v_rcp_f32_e32 v24, v14
	v_rcp_f32_e32 v40, v48
	v_rcp_f32_e32 v25, v49
	v_rcp_f32_e32 v41, v50
	v_rcp_f32_e32 v44, v45
	v_rcp_f32_e32 v45, v47
	v_pk_fma_f32 v[36:37], v[0:1], v[36:37], v[42:43] op_sel_hi:[0,1,1] neg_lo:[0,0,1] neg_hi:[0,0,1]
	v_pk_fma_f32 v[22:23], v[0:1], v[22:23], v[26:27] op_sel_hi:[0,1,1] neg_lo:[0,0,1] neg_hi:[0,0,1]
	v_pk_mul_f32 v[26:27], v[32:33], v[28:29]
	v_pk_mul_f32 v[12:13], v[12:13], v[20:21]
	v_pk_mul_f32 v[10:11], v[10:11], v[36:37]
	v_pk_mul_f32 v[8:9], v[8:9], v[22:23]
	v_pk_mul_f32 v[6:7], v[38:39], v[6:7]
	v_pk_mul_f32 v[20:21], v[24:25], v[34:35]
	v_pk_mul_f32 v[18:19], v[40:41], v[18:19]
	v_pk_mul_f32 v[16:17], v[44:45], v[16:17]
	v_pk_mul_f32 v[6:7], v[6:7], v[26:27]
	v_pk_mul_f32 v[10:11], v[20:21], v[10:11]
	v_pk_mul_f32 v[8:9], v[18:19], v[8:9]
	v_pk_mul_f32 v[12:13], v[16:17], v[12:13]
	v_bfe_u32 v0, v9, 16, 1
	v_bfe_u32 v18, v6, 16, 1
	v_bfe_u32 v19, v7, 16, 1
	v_bfe_u32 v20, v10, 16, 1
	v_bfe_u32 v21, v11, 16, 1
	v_bfe_u32 v14, v8, 16, 1
	v_bfe_u32 v16, v13, 16, 1
	v_bfe_u32 v17, v12, 16, 1
	v_add3_u32 v0, v9, v0, s12
	v_add3_u32 v9, v11, v21, s12
	v_add3_u32 v10, v10, v20, s12
	v_add3_u32 v7, v7, v19, s12
	v_add3_u32 v6, v6, v18, s12
	v_add3_u32 v12, v12, v17, s12
	v_add3_u32 v13, v13, v16, s12
	v_add3_u32 v8, v8, v14, s12
	v_lshrrev_b32_e32 v6, 16, v6
	v_lshrrev_b32_e32 v7, 16, v7
	v_lshrrev_b32_e32 v10, 16, v10
	v_lshrrev_b32_e32 v9, 16, v9
	v_and_or_b32 v9, v0, s11, v9
	v_and_or_b32 v8, v8, s11, v10
	v_and_or_b32 v7, v13, s11, v7
	v_and_or_b32 v6, v12, s11, v6
	global_store_dwordx4 v[30:31], v[6:9], off offset:2048
	s_andn2_b64 exec, exec, s[6:7]
	s_cbranch_execnz .LBB0_515
	s_or_b64 exec, exec, s[6:7]
	s_mov_b64 s[8:9], 0
	s_movk_i32 s1, 0x2000
	s_mov_b64 s[10:11], 0x1000
	v_mov_b32_e32 v1, 0
	s_movk_i32 s12, 0x1000
	s_mov_b32 s13, 0xffff0000
	s_movk_i32 s14, 0x7fff
	s_mov_b32 s15, s60
	v_mov_b32_e32 v4, 0x4000
	v_mov_b32_e32 v5, 0x800
	v_mov_b32_e32 v6, 0x200
	v_mov_b32_e32 v7, v15
	v_mov_b32_e32 v8, v212
.LBB0_517:
	v_ashrrev_i32_e32 v2, 5, v8
	v_and_b32_e32 v9, 0xf8, v7
	v_and_b32_e32 v10, 0x7ff, v2
	v_add_u32_e32 v11, 0xffffe000, v2
	v_cmp_gt_i32_e32 vcc, s1, v2
	v_add_u32_e32 v8, s61, v8
	v_lshl_or_b32 v0, v9, 1, v6
	v_lshlrev_b32_e32 v9, 2, v9
	v_cndmask_b32_e32 v32, v11, v10, vcc
	v_cndmask_b32_e32 v25, v4, v5, vcc
	v_ashrrev_i32_e32 v3, 31, v2
	v_cmp_lt_i32_e64 s[4:5], s15, v8
	global_load_dwordx4 v[10:13], v9, s[54:55] offset:1040
	global_load_dwordx4 v[16:19], v9, s[54:55] offset:1024
	v_add_u32_e32 v9, -2, v32
	v_lshlrev_b64 v[20:21], 13, v[2:3]
	s_or_b64 s[8:9], s[4:5], s[8:9]
	v_add_u32_e32 v29, -1, v32
	v_cmp_lt_u32_e64 s[4:5], v9, v25
	v_add_u32_e32 v30, 1, v32
	v_lshl_add_u64 v[20:21], s[44:45], 0, v[20:21]
	v_cndmask_b32_e64 v40, 0, 1.0, s[4:5]
	v_cmp_lt_u32_e64 s[4:5], v29, v25
	v_add_u32_e32 v27, -1, v25
	v_lshl_add_u64 v[20:21], v[20:21], 0, v[0:1]
	v_cndmask_b32_e64 v42, 0, 1.0, s[4:5]
	v_cmp_lt_u32_e64 s[4:5], v30, v25
	v_min_i32_e32 v22, v32, v27
	v_cmp_lt_u32_e32 vcc, v32, v25
	v_cndmask_b32_e64 v44, 0, 1.0, s[4:5]
	v_add_co_u32_e64 v46, s[4:5], s12, v20
	v_sub_u32_e32 v2, v2, v32
	v_cndmask_b32_e64 v14, 0, 1.0, vcc
	v_cmp_lt_i32_e32 vcc, v32, v27
	v_ashrrev_i32_e32 v23, 31, v22
	v_addc_co_u32_e64 v47, s[4:5], 0, v21, s[4:5]
	v_ashrrev_i32_e32 v3, 31, v2
	v_min_i32_e32 v24, v9, v27
	v_min_i32_e32 v26, v29, v27
	v_min_i32_e32 v28, v30, v27
	v_cndmask_b32_e32 v9, v27, v30, vcc
	v_lshlrev_b64 v[30:31], 12, v[22:23]
	global_load_dwordx4 v[20:23], v[46:47], off offset:2048
	v_lshlrev_b64 v[2:3], 13, v[2:3]
	v_ashrrev_i32_e32 v25, 31, v24
	v_ashrrev_i32_e32 v27, 31, v26
	v_cmp_lt_i32_e32 vcc, -1, v32
	v_ashrrev_i32_e32 v29, 31, v28
	v_lshl_add_u64 v[2:3], s[44:45], 0, v[2:3]
	v_lshlrev_b64 v[24:25], 12, v[24:25]
	v_cmp_lt_i32_e64 s[4:5], 1, v32
	v_lshlrev_b64 v[26:27], 12, v[26:27]
	v_cmp_lt_i32_e64 s[6:7], 0, v32
	v_cndmask_b32_e32 v31, 0, v31, vcc
	v_cndmask_b32_e32 v30, 0, v30, vcc
	v_lshlrev_b64 v[28:29], 12, v[28:29]
	v_cmp_lt_i32_e32 vcc, -2, v32
	v_lshl_add_u64 v[2:3], v[2:3], 0, s[10:11]
	v_cndmask_b32_e64 v25, 0, v25, s[4:5]
	v_cndmask_b32_e64 v24, 0, v24, s[4:5]
	v_cndmask_b32_e64 v27, 0, v27, s[6:7]
	v_cndmask_b32_e64 v26, 0, v26, s[6:7]
	v_cndmask_b32_e32 v29, 0, v29, vcc
	v_cndmask_b32_e32 v28, 0, v28, vcc
	v_lshl_add_u64 v[24:25], v[24:25], 1, v[2:3]
	v_lshl_add_u64 v[26:27], v[26:27], 1, v[2:3]
	v_lshl_add_u64 v[30:31], v[30:31], 1, v[2:3]
	v_max_i32_e32 v33, 2, v32
	v_lshl_add_u64 v[2:3], v[28:29], 1, v[2:3]
	v_lshl_add_u64 v[24:25], v[24:25], 0, v[0:1]
	v_lshl_add_u64 v[28:29], v[26:27], 0, v[0:1]
	v_lshl_add_u64 v[36:37], v[30:31], 0, v[0:1]
	v_sub_u32_e32 v9, v9, v33
	v_lshl_add_u64 v[2:3], v[2:3], 0, v[0:1]
	global_load_dwordx4 v[24:27], v[24:25], off
	s_nop 0
	global_load_dwordx4 v[28:31], v[28:29], off
	s_nop 0
	global_load_dwordx4 v[32:35], v[2:3], off
	s_nop 0
	global_load_dwordx4 v[36:39], v[36:37], off
	v_add_u32_e32 v9, 3, v9
	v_cvt_f32_i32_e32 v9, v9
	v_add_u32_e32 v7, s0, v7
	v_div_scale_f32 v0, s[4:5], v9, v9, 1.0
	v_rcp_f32_e32 v3, v0
	v_div_scale_f32 v2, vcc, 1.0, v9, 1.0
	v_fma_f32 v41, -v0, v3, 1.0
	v_fmac_f32_e32 v3, v41, v3
	v_mul_f32_e32 v41, v2, v3
	v_fma_f32 v43, -v0, v41, v2
	v_fmac_f32_e32 v41, v43, v3
	v_fma_f32 v0, -v0, v41, v2
	v_div_fmas_f32 v0, v0, v3, v41
	s_waitcnt vmcnt(5)
	v_mov_b32_e32 v2, v16
	v_mov_b32_e32 v3, v18
	v_mov_b32_e32 v18, v17
	v_mov_b32_e32 v16, v10
	v_mov_b32_e32 v17, v12
	v_mov_b32_e32 v12, v11
	v_div_fixup_f32 v0, v0, v9, 1.0
	s_waitcnt vmcnt(4)
	v_lshlrev_b32_e32 v11, 16, v21
	v_lshlrev_b32_e32 v10, 16, v20
	v_lshlrev_b32_e32 v49, 16, v23
	v_lshlrev_b32_e32 v48, 16, v22
	v_and_b32_e32 v23, 0xffff0000, v23
	v_and_b32_e32 v22, 0xffff0000, v22
	v_and_b32_e32 v21, 0xffff0000, v21
	v_and_b32_e32 v20, 0xffff0000, v20
	v_mul_f32_e32 v9, 0xbfb8aa3b, v10
	v_mul_f32_e32 v43, 0xbfb8aa3b, v11
	v_mul_f32_e32 v50, 0xbfb8aa3b, v48
	v_mul_f32_e32 v51, 0xbfb8aa3b, v22
	v_mul_f32_e32 v52, 0xbfb8aa3b, v49
	v_mul_f32_e32 v53, 0xbfb8aa3b, v23
	v_mul_f32_e32 v41, 0xbfb8aa3b, v20
	v_mul_f32_e32 v45, 0xbfb8aa3b, v21
	v_exp_f32_e32 v9, v9
	v_exp_f32_e32 v43, v43
	v_exp_f32_e32 v67, v50
	v_exp_f32_e32 v68, v51
	v_exp_f32_e32 v69, v52
	v_exp_f32_e32 v70, v53
	v_exp_f32_e32 v66, v41
	v_exp_f32_e32 v45, v45
	v_add_f32_e32 v9, 1.0, v9
	v_add_f32_e32 v45, 1.0, v45
	s_waitcnt vmcnt(3)
	v_lshlrev_b32_e32 v51, 16, v25
	v_lshlrev_b32_e32 v50, 16, v24
	v_and_b32_e32 v25, 0xffff0000, v25
	v_and_b32_e32 v24, 0xffff0000, v24
	v_lshlrev_b32_e32 v55, 16, v27
	v_lshlrev_b32_e32 v54, 16, v26
	v_and_b32_e32 v27, 0xffff0000, v27
	v_and_b32_e32 v26, 0xffff0000, v26
	s_waitcnt vmcnt(2)
	v_lshlrev_b32_e32 v53, 16, v29
	v_lshlrev_b32_e32 v52, 16, v28
	v_and_b32_e32 v29, 0xffff0000, v29
	v_and_b32_e32 v28, 0xffff0000, v28
	v_lshlrev_b32_e32 v57, 16, v31
	v_lshlrev_b32_e32 v56, 16, v30
	v_and_b32_e32 v31, 0xffff0000, v31
	v_and_b32_e32 v30, 0xffff0000, v30
	v_pk_fma_f32 v[50:51], v[40:41], v[50:51], 0 op_sel_hi:[0,1,0]
	v_pk_fma_f32 v[24:25], v[40:41], v[24:25], 0 op_sel_hi:[0,1,0]
	v_pk_fma_f32 v[54:55], v[40:41], v[54:55], 0 op_sel_hi:[0,1,0]
	v_pk_fma_f32 v[26:27], v[40:41], v[26:27], 0 op_sel_hi:[0,1,0]
	s_waitcnt vmcnt(0)
	v_lshlrev_b32_e32 v63, 16, v37
	v_lshlrev_b32_e32 v62, 16, v36
	v_pk_fma_f32 v[40:41], v[42:43], v[52:53], v[50:51] op_sel_hi:[0,1,1]
	v_pk_fma_f32 v[24:25], v[42:43], v[28:29], v[24:25] op_sel_hi:[0,1,1]
	v_pk_fma_f32 v[28:29], v[42:43], v[56:57], v[54:55] op_sel_hi:[0,1,1]
	v_pk_fma_f32 v[26:27], v[42:43], v[30:31], v[26:27] op_sel_hi:[0,1,1]
	v_add_f32_e32 v43, 1.0, v43
	v_add_f32_e32 v50, 1.0, v67
	v_add_f32_e32 v51, 1.0, v68
	v_add_f32_e32 v53, 1.0, v69
	v_add_f32_e32 v54, 1.0, v70
	v_and_b32_e32 v37, 0xffff0000, v37
	v_and_b32_e32 v36, 0xffff0000, v36
	v_lshlrev_b32_e32 v65, 16, v39
	v_lshlrev_b32_e32 v64, 16, v38
	v_and_b32_e32 v39, 0xffff0000, v39
	v_and_b32_e32 v38, 0xffff0000, v38
	v_add_f32_e32 v42, 1.0, v66
	v_pk_fma_f32 v[30:31], v[14:15], v[62:63], v[40:41] op_sel_hi:[0,1,1]
	v_rcp_f32_e32 v40, v9
	v_rcp_f32_e32 v41, v43
	v_rcp_f32_e32 v50, v50
	v_rcp_f32_e32 v52, v51
	v_rcp_f32_e32 v51, v53
	v_rcp_f32_e32 v53, v54
	v_lshlrev_b32_e32 v59, 16, v33
	v_lshlrev_b32_e32 v58, 16, v32
	v_and_b32_e32 v33, 0xffff0000, v33
	v_and_b32_e32 v32, 0xffff0000, v32
	v_lshlrev_b32_e32 v61, 16, v35
	v_lshlrev_b32_e32 v60, 16, v34
	v_and_b32_e32 v35, 0xffff0000, v35
	v_and_b32_e32 v34, 0xffff0000, v34
	v_pk_fma_f32 v[24:25], v[14:15], v[36:37], v[24:25] op_sel_hi:[0,1,1]
	v_rcp_f32_e32 v42, v42
	v_rcp_f32_e32 v43, v45
	v_pk_fma_f32 v[28:29], v[14:15], v[64:65], v[28:29] op_sel_hi:[0,1,1]
	v_pk_fma_f32 v[26:27], v[14:15], v[38:39], v[26:27] op_sel_hi:[0,1,1]
	v_pk_fma_f32 v[30:31], v[44:45], v[58:59], v[30:31] op_sel_hi:[0,1,1]
	v_pk_fma_f32 v[24:25], v[44:45], v[32:33], v[24:25] op_sel_hi:[0,1,1]
	v_pk_fma_f32 v[28:29], v[44:45], v[60:61], v[28:29] op_sel_hi:[0,1,1]
	v_pk_fma_f32 v[26:27], v[44:45], v[34:35], v[26:27] op_sel_hi:[0,1,1]
	v_pk_fma_f32 v[30:31], v[0:1], v[30:31], v[62:63] op_sel_hi:[0,1,1] neg_lo:[0,0,1] neg_hi:[0,0,1]
	v_pk_fma_f32 v[24:25], v[0:1], v[24:25], v[36:37] op_sel_hi:[0,1,1] neg_lo:[0,0,1] neg_hi:[0,0,1]
	v_pk_fma_f32 v[28:29], v[0:1], v[28:29], v[64:65] op_sel_hi:[0,1,1] neg_lo:[0,0,1] neg_hi:[0,0,1]
	v_pk_fma_f32 v[26:27], v[0:1], v[26:27], v[38:39] op_sel_hi:[0,1,1] neg_lo:[0,0,1] neg_hi:[0,0,1]
	v_pk_mul_f32 v[2:3], v[2:3], v[30:31]
	v_pk_mul_f32 v[18:19], v[18:19], v[24:25]
	v_pk_mul_f32 v[16:17], v[16:17], v[28:29]
	v_pk_mul_f32 v[12:13], v[12:13], v[26:27]
	v_pk_mul_f32 v[10:11], v[40:41], v[10:11]
	v_pk_mul_f32 v[24:25], v[50:51], v[48:49]
	v_pk_mul_f32 v[22:23], v[52:53], v[22:23]
	v_pk_mul_f32 v[20:21], v[42:43], v[20:21]
	v_pk_mul_f32 v[2:3], v[10:11], v[2:3]
	v_pk_mul_f32 v[16:17], v[24:25], v[16:17]
	v_pk_mul_f32 v[12:13], v[22:23], v[12:13]
	v_pk_mul_f32 v[10:11], v[20:21], v[18:19]
	v_bfe_u32 v0, v13, 16, 1
	v_bfe_u32 v9, v12, 16, 1
	v_bfe_u32 v19, v2, 16, 1
	v_bfe_u32 v20, v3, 16, 1
	v_bfe_u32 v21, v16, 16, 1
	v_bfe_u32 v22, v17, 16, 1
	v_bfe_u32 v14, v11, 16, 1
	v_bfe_u32 v18, v10, 16, 1
	v_add3_u32 v9, v12, v9, s14
	v_add3_u32 v0, v13, v0, s14
	v_add3_u32 v12, v17, v22, s14
	v_add3_u32 v13, v16, v21, s14
	v_add3_u32 v3, v3, v20, s14
	v_add3_u32 v2, v2, v19, s14
	v_add3_u32 v10, v10, v18, s14
	v_add3_u32 v11, v11, v14, s14
	v_lshrrev_b32_e32 v2, 16, v2
	v_lshrrev_b32_e32 v3, 16, v3
	v_lshrrev_b32_e32 v14, 16, v13
	v_lshrrev_b32_e32 v12, 16, v12
	v_and_or_b32 v13, v0, s13, v12
	v_and_or_b32 v12, v9, s13, v14
	v_and_or_b32 v11, v11, s13, v3
	v_and_or_b32 v10, v10, s13, v2
	global_store_dwordx4 v[46:47], v[10:13], off offset:2048
	s_andn2_b64 exec, exec, s[8:9]
	s_cbranch_execnz .LBB0_517
	s_or_b64 exec, exec, s[8:9]
	s_mov_b64 s[16:17], 0
	s_movk_i32 s1, 0x2000
	s_mov_b64 s[18:19], 0x1000
	v_mov_b32_e32 v9, 0
	s_movk_i32 s20, 0x1000
	s_mov_b32 s21, 0xffff0000
	s_movk_i32 s22, 0x7fff
	s_mov_b32 s23, s60
	v_mov_b32_e32 v12, 0x4000
	v_mov_b32_e32 v13, 0x800
	v_mov_b32_e32 v14, 0x400
	v_mov_b32_e32 v16, v15
	v_mov_b32_e32 v17, v212
.LBB0_519:
	v_ashrrev_i32_e32 v10, 5, v17
	v_and_b32_e32 v1, 0x7ff, v10
	v_add_u32_e32 v2, 0xffffe000, v10
	v_cmp_gt_i32_e32 vcc, s1, v10
	v_ashrrev_i32_e32 v11, 31, v10
	v_and_b32_e32 v0, 0xf8, v16
	v_cndmask_b32_e32 v23, v12, v13, vcc
	v_cndmask_b32_e32 v40, v2, v1, vcc
	v_add_u32_e32 v27, -4, v40
	v_cmp_lt_u32_e32 vcc, v40, v23
	v_add_u32_e32 v29, -3, v40
	v_add_u32_e32 v31, -2, v40
	v_cndmask_b32_e64 v54, 0, 1.0, vcc
	v_cmp_lt_u32_e32 vcc, v27, v23
	v_add_u32_e32 v33, -1, v40
	v_lshlrev_b64 v[18:19], 13, v[10:11]
	v_cndmask_b32_e64 v56, 0, 1.0, vcc
	v_cmp_lt_u32_e32 vcc, v29, v23
	v_add_u32_e32 v35, 1, v40
	v_add_u32_e32 v17, s61, v17
	v_cndmask_b32_e64 v58, 0, 1.0, vcc
	v_cmp_lt_u32_e32 vcc, v31, v23
	v_lshl_or_b32 v8, v0, 1, v14
	v_add_u32_e32 v25, -1, v23
	v_cndmask_b32_e64 v60, 0, 1.0, vcc
	v_cmp_lt_u32_e32 vcc, v33, v23
	v_sub_u32_e32 v10, v10, v40
	v_add_u32_e32 v36, 2, v40
	v_lshl_add_u64 v[18:19], s[44:45], 0, v[18:19]
	v_cndmask_b32_e64 v62, 0, 1.0, vcc
	v_cmp_lt_u32_e32 vcc, v35, v23
	v_cmp_lt_i32_e64 s[4:5], s23, v17
	v_min_i32_e32 v20, v40, v25
	v_add_u32_e32 v37, 3, v40
	v_ashrrev_i32_e32 v11, 31, v10
	v_lshl_add_u64 v[18:19], v[18:19], 0, v[8:9]
	v_cndmask_b32_e64 v64, 0, 1.0, vcc
	v_cmp_lt_u32_e32 vcc, v36, v23
	s_or_b64 s[16:17], s[4:5], s[16:17]
	v_ashrrev_i32_e32 v21, 31, v20
	v_min_i32_e32 v32, v36, v25
	v_min_i32_e32 v34, v37, v25
	v_cndmask_b32_e64 v66, 0, 1.0, vcc
	v_cmp_lt_u32_e32 vcc, v37, v23
	v_lshlrev_b64 v[36:37], 13, v[10:11]
	v_add_co_u32_e64 v10, s[4:5], s20, v18
	v_lshlrev_b32_e32 v4, 2, v0
	v_max_i32_e32 v38, 4, v40
	v_cndmask_b32_e64 v68, 0, 1.0, vcc
	v_lshlrev_b64 v[20:21], 12, v[20:21]
	v_cmp_lt_i32_e32 vcc, -1, v40
	v_addc_co_u32_e64 v11, s[4:5], 0, v19, s[4:5]
	global_load_dwordx4 v[0:3], v4, s[54:55] offset:2064
	s_nop 0
	global_load_dwordx4 v[4:7], v4, s[54:55] offset:2048
	v_sub_u32_e32 v41, v34, v38
	v_cndmask_b32_e32 v39, 0, v21, vcc
	v_cndmask_b32_e32 v38, 0, v20, vcc
	global_load_dwordx4 v[18:21], v[10:11], off offset:2048
	v_min_i32_e32 v22, v27, v25
	v_min_i32_e32 v24, v29, v25
	v_min_i32_e32 v26, v31, v25
	v_min_i32_e32 v28, v33, v25
	v_min_i32_e32 v30, v35, v25
	v_ashrrev_i32_e32 v23, 31, v22
	v_ashrrev_i32_e32 v25, 31, v24
	v_ashrrev_i32_e32 v27, 31, v26
	v_ashrrev_i32_e32 v29, 31, v28
	v_ashrrev_i32_e32 v31, 31, v30
	v_ashrrev_i32_e32 v33, 31, v32
	v_ashrrev_i32_e32 v35, 31, v34
	v_lshl_add_u64 v[36:37], s[44:45], 0, v[36:37]
	v_lshlrev_b64 v[22:23], 12, v[22:23]
	v_cmp_lt_i32_e64 s[4:5], 3, v40
	v_lshlrev_b64 v[24:25], 12, v[24:25]
	v_cmp_lt_i32_e64 s[6:7], 2, v40
	v_lshlrev_b64 v[26:27], 12, v[26:27]
	v_cmp_lt_i32_e64 s[8:9], 1, v40
	v_lshlrev_b64 v[28:29], 12, v[28:29]
	v_cmp_lt_i32_e64 s[10:11], 0, v40
	v_lshlrev_b64 v[30:31], 12, v[30:31]
	v_cmp_lt_i32_e32 vcc, -2, v40
	v_lshlrev_b64 v[32:33], 12, v[32:33]
	v_cmp_lt_i32_e64 s[12:13], -3, v40
	v_lshlrev_b64 v[34:35], 12, v[34:35]
	v_cmp_lt_i32_e64 s[14:15], -4, v40
	v_lshl_add_u64 v[36:37], v[36:37], 0, s[18:19]
	v_cndmask_b32_e64 v23, 0, v23, s[4:5]
	v_cndmask_b32_e64 v22, 0, v22, s[4:5]
	v_cndmask_b32_e64 v25, 0, v25, s[6:7]
	v_cndmask_b32_e64 v24, 0, v24, s[6:7]
	v_cndmask_b32_e64 v27, 0, v27, s[8:9]
	v_cndmask_b32_e64 v26, 0, v26, s[8:9]
	v_cndmask_b32_e64 v29, 0, v29, s[10:11]
	v_cndmask_b32_e64 v28, 0, v28, s[10:11]
	v_cndmask_b32_e32 v31, 0, v31, vcc
	v_cndmask_b32_e32 v30, 0, v30, vcc
	v_cndmask_b32_e64 v33, 0, v33, s[12:13]
	v_cndmask_b32_e64 v32, 0, v32, s[12:13]
	v_cndmask_b32_e64 v35, 0, v35, s[14:15]
	v_cndmask_b32_e64 v34, 0, v34, s[14:15]
	v_add_u32_e32 v40, 5, v41
	v_lshl_add_u64 v[22:23], v[22:23], 1, v[36:37]
	v_lshl_add_u64 v[24:25], v[24:25], 1, v[36:37]
	v_lshl_add_u64 v[26:27], v[26:27], 1, v[36:37]
	v_lshl_add_u64 v[28:29], v[28:29], 1, v[36:37]
	v_lshl_add_u64 v[38:39], v[38:39], 1, v[36:37]
	v_lshl_add_u64 v[30:31], v[30:31], 1, v[36:37]
	v_lshl_add_u64 v[32:33], v[32:33], 1, v[36:37]
	v_lshl_add_u64 v[34:35], v[34:35], 1, v[36:37]
	v_cvt_f32_i32_e32 v55, v40
	v_lshl_add_u64 v[36:37], v[22:23], 0, v[8:9]
	v_lshl_add_u64 v[40:41], v[24:25], 0, v[8:9]
	v_lshl_add_u64 v[42:43], v[26:27], 0, v[8:9]
	v_lshl_add_u64 v[46:47], v[28:29], 0, v[8:9]
	v_lshl_add_u64 v[38:39], v[38:39], 0, v[8:9]
	v_lshl_add_u64 v[50:51], v[30:31], 0, v[8:9]
	v_lshl_add_u64 v[22:23], v[32:33], 0, v[8:9]
	v_lshl_add_u64 v[26:27], v[34:35], 0, v[8:9]
	global_load_dwordx4 v[22:25], v[22:23], off
	s_nop 0
	global_load_dwordx4 v[26:29], v[26:27], off
	s_nop 0
	global_load_dwordx4 v[30:33], v[38:39], off
	s_nop 0
	global_load_dwordx4 v[34:37], v[36:37], off
	s_nop 0
	global_load_dwordx4 v[38:41], v[40:41], off
	s_nop 0
	global_load_dwordx4 v[42:45], v[42:43], off
	s_nop 0
	global_load_dwordx4 v[46:49], v[46:47], off
	s_nop 0
	global_load_dwordx4 v[50:53], v[50:51], off
	v_div_scale_f32 v8, s[4:5], v55, v55, 1.0
	v_rcp_f32_e32 v59, v8
	v_div_scale_f32 v57, vcc, 1.0, v55, 1.0
	v_add_u32_e32 v16, s0, v16
	v_fma_f32 v61, -v8, v59, 1.0
	v_fmac_f32_e32 v59, v61, v59
	v_mul_f32_e32 v61, v57, v59
	v_fma_f32 v63, -v8, v61, v57
	v_fmac_f32_e32 v61, v63, v59
	v_fma_f32 v8, -v8, v61, v57
	v_div_fmas_f32 v8, v8, v59, v61
	v_div_fixup_f32 v8, v8, v55, 1.0
	s_waitcnt vmcnt(9)
	v_mov_b32_e32 v71, v6
	v_mov_b32_e32 v6, v5
	v_mov_b32_e32 v5, v2
	v_mov_b32_e32 v2, v1
	s_waitcnt vmcnt(8)
	v_lshlrev_b32_e32 v1, 16, v19
	v_and_b32_e32 v19, 0xffff0000, v19
	v_mul_f32_e32 v59, 0xbfb8aa3b, v1
	v_lshlrev_b32_e32 v72, 16, v20
	v_and_b32_e32 v20, 0xffff0000, v20
	v_mul_f32_e32 v61, 0xbfb8aa3b, v19
	v_exp_f32_e32 v59, v59
	v_mov_b32_e32 v70, v4
	v_mov_b32_e32 v4, v0
	v_lshlrev_b32_e32 v0, 16, v18
	v_and_b32_e32 v18, 0xffff0000, v18
	v_mul_f32_e32 v63, 0xbfb8aa3b, v72
	v_mul_f32_e32 v65, 0xbfb8aa3b, v20
	v_exp_f32_e32 v61, v61
	v_lshlrev_b32_e32 v73, 16, v21
	v_mul_f32_e32 v55, 0xbfb8aa3b, v0
	v_mul_f32_e32 v57, 0xbfb8aa3b, v18
	v_exp_f32_e32 v63, v63
	v_exp_f32_e32 v65, v65
	v_and_b32_e32 v21, 0xffff0000, v21
	v_mul_f32_e32 v67, 0xbfb8aa3b, v73
	v_exp_f32_e32 v55, v55
	v_mul_f32_e32 v69, 0xbfb8aa3b, v21
	v_exp_f32_e32 v106, v57
	v_exp_f32_e32 v67, v67
	v_exp_f32_e32 v69, v69
	v_add_f32_e32 v61, 1.0, v61
	v_add_f32_e32 v55, 1.0, v55
	s_waitcnt vmcnt(7)
	v_lshlrev_b32_e32 v75, 16, v23
	v_lshlrev_b32_e32 v74, 16, v22
	s_waitcnt vmcnt(5)
	v_lshlrev_b32_e32 v83, 16, v31
	s_waitcnt vmcnt(4)
	v_lshlrev_b32_e32 v85, 16, v35
	v_lshlrev_b32_e32 v84, 16, v34
	v_and_b32_e32 v35, 0xffff0000, v35
	v_and_b32_e32 v34, 0xffff0000, v34
	s_waitcnt vmcnt(3)
	v_lshlrev_b32_e32 v87, 16, v39
	v_lshlrev_b32_e32 v86, 16, v38
	v_and_b32_e32 v39, 0xffff0000, v39
	v_and_b32_e32 v38, 0xffff0000, v38
	v_lshlrev_b32_e32 v97, 16, v37
	v_lshlrev_b32_e32 v96, 16, v36
	v_and_b32_e32 v37, 0xffff0000, v37
	v_and_b32_e32 v36, 0xffff0000, v36
	v_pk_fma_f32 v[84:85], v[56:57], v[84:85], 0 op_sel_hi:[0,1,0]
	v_pk_fma_f32 v[34:35], v[56:57], v[34:35], 0 op_sel_hi:[0,1,0]
	v_lshlrev_b32_e32 v99, 16, v41
	v_lshlrev_b32_e32 v98, 16, v40
	v_pk_fma_f32 v[96:97], v[56:57], v[96:97], 0 op_sel_hi:[0,1,0]
	v_pk_fma_f32 v[36:37], v[56:57], v[36:37], 0 op_sel_hi:[0,1,0]
	v_pk_fma_f32 v[56:57], v[58:59], v[86:87], v[84:85] op_sel_hi:[0,1,1]
	v_pk_fma_f32 v[34:35], v[58:59], v[38:39], v[34:35] op_sel_hi:[0,1,1]
	v_add_f32_e32 v59, 1.0, v59
	s_waitcnt vmcnt(2)
	v_lshlrev_b32_e32 v89, 16, v43
	v_lshlrev_b32_e32 v88, 16, v42
	v_and_b32_e32 v43, 0xffff0000, v43
	v_and_b32_e32 v42, 0xffff0000, v42
	v_lshlrev_b32_e32 v101, 16, v45
	v_lshlrev_b32_e32 v100, 16, v44
	v_and_b32_e32 v41, 0xffff0000, v41
	v_and_b32_e32 v40, 0xffff0000, v40
	v_pk_fma_f32 v[38:39], v[58:59], v[98:99], v[96:97] op_sel_hi:[0,1,1]
	s_waitcnt vmcnt(1)
	v_lshlrev_b32_e32 v91, 16, v47
	v_lshlrev_b32_e32 v90, 16, v46
	v_and_b32_e32 v47, 0xffff0000, v47
	v_and_b32_e32 v46, 0xffff0000, v46
	v_lshlrev_b32_e32 v103, 16, v49
	v_lshlrev_b32_e32 v102, 16, v48
	v_and_b32_e32 v45, 0xffff0000, v45
	v_and_b32_e32 v44, 0xffff0000, v44
	v_pk_fma_f32 v[36:37], v[58:59], v[40:41], v[36:37] op_sel_hi:[0,1,1]
	v_add_f32_e32 v58, 1.0, v63
	v_add_f32_e32 v63, 1.0, v65
	v_pk_fma_f32 v[40:41], v[60:61], v[88:89], v[56:57] op_sel_hi:[0,1,1]
	v_pk_fma_f32 v[34:35], v[60:61], v[42:43], v[34:35] op_sel_hi:[0,1,1]
	v_pk_fma_f32 v[38:39], v[60:61], v[100:101], v[38:39] op_sel_hi:[0,1,1]
	v_lshlrev_b32_e32 v82, 16, v30
	v_and_b32_e32 v31, 0xffff0000, v31
	v_and_b32_e32 v30, 0xffff0000, v30
	v_lshlrev_b32_e32 v95, 16, v33
	v_lshlrev_b32_e32 v94, 16, v32
	v_and_b32_e32 v49, 0xffff0000, v49
	v_and_b32_e32 v48, 0xffff0000, v48
	v_pk_fma_f32 v[36:37], v[60:61], v[44:45], v[36:37] op_sel_hi:[0,1,1]
	v_pk_fma_f32 v[40:41], v[62:63], v[90:91], v[40:41] op_sel_hi:[0,1,1]
	v_pk_fma_f32 v[34:35], v[62:63], v[46:47], v[34:35] op_sel_hi:[0,1,1]
	v_pk_fma_f32 v[38:39], v[62:63], v[102:103], v[38:39] op_sel_hi:[0,1,1]
	s_waitcnt vmcnt(0)
	v_lshlrev_b32_e32 v93, 16, v51
	v_lshlrev_b32_e32 v92, 16, v50
	v_and_b32_e32 v51, 0xffff0000, v51
	v_and_b32_e32 v50, 0xffff0000, v50
	v_and_b32_e32 v33, 0xffff0000, v33
	v_and_b32_e32 v32, 0xffff0000, v32
	v_lshlrev_b32_e32 v105, 16, v53
	v_lshlrev_b32_e32 v104, 16, v52
	v_add_f32_e32 v65, 1.0, v67
	v_pk_fma_f32 v[36:37], v[62:63], v[48:49], v[36:37] op_sel_hi:[0,1,1]
	v_pk_fma_f32 v[40:41], v[54:55], v[82:83], v[40:41] op_sel_hi:[0,1,1]
	v_pk_fma_f32 v[34:35], v[54:55], v[30:31], v[34:35] op_sel_hi:[0,1,1]
	v_pk_fma_f32 v[38:39], v[54:55], v[94:95], v[38:39] op_sel_hi:[0,1,1]
	v_and_b32_e32 v23, 0xffff0000, v23
	v_and_b32_e32 v22, 0xffff0000, v22
	v_lshlrev_b32_e32 v77, 16, v25
	v_lshlrev_b32_e32 v76, 16, v24
	v_and_b32_e32 v53, 0xffff0000, v53
	v_and_b32_e32 v52, 0xffff0000, v52
	v_add_f32_e32 v84, 1.0, v106
	v_add_f32_e32 v67, 1.0, v69
	v_rcp_f32_e32 v42, v55
	v_rcp_f32_e32 v43, v59
	v_rcp_f32_e32 v44, v58
	v_rcp_f32_e32 v45, v65
	v_pk_fma_f32 v[36:37], v[54:55], v[32:33], v[36:37] op_sel_hi:[0,1,1]
	v_pk_fma_f32 v[40:41], v[64:65], v[92:93], v[40:41] op_sel_hi:[0,1,1]
	v_pk_fma_f32 v[34:35], v[64:65], v[50:51], v[34:35] op_sel_hi:[0,1,1]
	v_pk_fma_f32 v[38:39], v[64:65], v[104:105], v[38:39] op_sel_hi:[0,1,1]
	v_and_b32_e32 v25, 0xffff0000, v25
	v_and_b32_e32 v24, 0xffff0000, v24
	v_lshlrev_b32_e32 v79, 16, v27
	v_lshlrev_b32_e32 v78, 16, v26
	v_and_b32_e32 v27, 0xffff0000, v27
	v_and_b32_e32 v26, 0xffff0000, v26
	v_lshlrev_b32_e32 v81, 16, v29
	v_lshlrev_b32_e32 v80, 16, v28
	v_rcp_f32_e32 v56, v84
	v_rcp_f32_e32 v57, v61
	v_rcp_f32_e32 v58, v63
	v_rcp_f32_e32 v59, v67
	v_pk_fma_f32 v[36:37], v[64:65], v[52:53], v[36:37] op_sel_hi:[0,1,1]
	v_pk_fma_f32 v[40:41], v[66:67], v[74:75], v[40:41] op_sel_hi:[0,1,1]
	v_pk_fma_f32 v[22:23], v[66:67], v[22:23], v[34:35] op_sel_hi:[0,1,1]
	v_pk_fma_f32 v[34:35], v[66:67], v[76:77], v[38:39] op_sel_hi:[0,1,1]
	v_and_b32_e32 v29, 0xffff0000, v29
	v_and_b32_e32 v28, 0xffff0000, v28
	v_pk_fma_f32 v[24:25], v[66:67], v[24:25], v[36:37] op_sel_hi:[0,1,1]
	v_pk_fma_f32 v[38:39], v[68:69], v[78:79], v[40:41] op_sel_hi:[0,1,1]
	v_pk_fma_f32 v[22:23], v[68:69], v[26:27], v[22:23] op_sel_hi:[0,1,1]
	v_pk_fma_f32 v[26:27], v[68:69], v[80:81], v[34:35] op_sel_hi:[0,1,1]
	v_pk_fma_f32 v[24:25], v[68:69], v[28:29], v[24:25] op_sel_hi:[0,1,1]
	v_pk_fma_f32 v[28:29], v[8:9], v[38:39], v[82:83] op_sel_hi:[0,1,1] neg_lo:[0,0,1] neg_hi:[0,0,1]
	v_pk_fma_f32 v[26:27], v[8:9], v[26:27], v[94:95] op_sel_hi:[0,1,1] neg_lo:[0,0,1] neg_hi:[0,0,1]
	v_pk_mul_f32 v[0:1], v[42:43], v[0:1]
	v_pk_mul_f32 v[36:37], v[44:45], v[72:73]
	v_pk_fma_f32 v[22:23], v[8:9], v[22:23], v[30:31] op_sel_hi:[0,1,1] neg_lo:[0,0,1] neg_hi:[0,0,1]
	v_pk_fma_f32 v[24:25], v[8:9], v[24:25], v[32:33] op_sel_hi:[0,1,1] neg_lo:[0,0,1] neg_hi:[0,0,1]
	v_pk_mul_f32 v[28:29], v[70:71], v[28:29]
	v_pk_mul_f32 v[4:5], v[4:5], v[26:27]
	v_pk_mul_f32 v[18:19], v[56:57], v[18:19]
	v_pk_mul_f32 v[20:21], v[58:59], v[20:21]
	v_pk_mul_f32 v[6:7], v[6:7], v[22:23]
	v_pk_mul_f32 v[2:3], v[2:3], v[24:25]
	v_pk_mul_f32 v[0:1], v[0:1], v[28:29]
	v_pk_mul_f32 v[4:5], v[36:37], v[4:5]
	v_pk_mul_f32 v[6:7], v[18:19], v[6:7]
	v_pk_mul_f32 v[2:3], v[20:21], v[2:3]
	v_bfe_u32 v21, v0, 16, 1
	v_bfe_u32 v22, v1, 16, 1
	v_bfe_u32 v23, v4, 16, 1
	v_bfe_u32 v24, v5, 16, 1
	v_bfe_u32 v8, v3, 16, 1
	v_bfe_u32 v18, v2, 16, 1
	v_bfe_u32 v19, v7, 16, 1
	v_bfe_u32 v20, v6, 16, 1
	v_add3_u32 v5, v5, v24, s22
	v_add3_u32 v4, v4, v23, s22
	v_add3_u32 v1, v1, v22, s22
	v_add3_u32 v0, v0, v21, s22
	v_add3_u32 v6, v6, v20, s22
	v_add3_u32 v7, v7, v19, s22
	v_add3_u32 v2, v2, v18, s22
	v_add3_u32 v3, v3, v8, s22
	v_lshrrev_b32_e32 v0, 16, v0
	v_lshrrev_b32_e32 v1, 16, v1
	v_lshrrev_b32_e32 v4, 16, v4
	v_lshrrev_b32_e32 v5, 16, v5
	v_and_or_b32 v3, v3, s21, v5
	v_and_or_b32 v2, v2, s21, v4
	v_and_or_b32 v1, v7, s21, v1
	v_and_or_b32 v0, v6, s21, v0
	global_store_dwordx4 v[10:11], v[0:3], off offset:2048
	s_andn2_b64 exec, exec, s[16:17]
	s_cbranch_execnz .LBB0_519
	s_or_b64 exec, exec, s[16:17]
	s_mov_b64 s[34:35], 0
	s_movk_i32 s1, 0x2000
	s_mov_b64 s[36:37], 0x1000
	v_mov_b32_e32 v9, 0
	s_movk_i32 s33, 0x1000
	s_mov_b32 s38, 0xffff0000
	s_movk_i32 s39, 0x7fff
	s_mov_b32 s40, s60
	v_mov_b32_e32 v17, 0x4000
	v_mov_b32_e32 v19, 0x800
	v_mov_b32_e32 v21, 0x600
	v_mov_b32_e32 v23, v212
.LBB0_521:
	v_ashrrev_i32_e32 v10, 5, v23
	v_and_b32_e32 v1, 0x7ff, v10
	v_add_u32_e32 v2, 0xffffe000, v10
	v_cmp_gt_i32_e32 vcc, s1, v10
	v_ashrrev_i32_e32 v11, 31, v10
	v_lshlrev_b64 v[12:13], 13, v[10:11]
	v_cndmask_b32_e32 v14, v17, v19, vcc
	v_cndmask_b32_e32 v25, v2, v1, vcc
	v_add_u32_e32 v11, -8, v25
	v_cmp_lt_u32_e32 vcc, v25, v14
	v_sub_u32_e32 v44, v10, v25
	v_add_u32_e32 v18, -7, v25
	v_cndmask_b32_e64 v10, 0, 1.0, vcc
	v_cmp_lt_u32_e32 vcc, v11, v14
	v_add_u32_e32 v20, -6, v25
	v_add_u32_e32 v22, -5, v25
	v_cndmask_b32_e64 v42, 0, 1.0, vcc
	v_cmp_lt_u32_e32 vcc, v18, v14
	v_add_u32_e32 v24, -4, v25
	v_add_u32_e32 v26, -3, v25
	v_cndmask_b32_e64 v40, 0, 1.0, vcc
	v_cmp_lt_u32_e32 vcc, v20, v14
	v_add_u32_e32 v27, -2, v25
	v_add_u32_e32 v28, -1, v25
	v_cndmask_b32_e64 v38, 0, 1.0, vcc
	v_cmp_lt_u32_e32 vcc, v22, v14
	v_add_u32_e32 v16, -1, v14
	v_add_u32_e32 v29, 1, v25
	v_cndmask_b32_e64 v36, 0, 1.0, vcc
	v_cmp_lt_u32_e32 vcc, v24, v14
	v_add_u32_e32 v31, 2, v25
	v_min_i32_e32 v62, v28, v16
	v_cndmask_b32_e64 v34, 0, 1.0, vcc
	v_cmp_lt_u32_e32 vcc, v26, v14
	v_add_u32_e32 v33, 3, v25
	v_min_i32_e32 v58, v26, v16
	v_cndmask_b32_e64 v32, 0, 1.0, vcc
	v_cmp_lt_u32_e32 vcc, v27, v14
	v_add_u32_e32 v35, 4, v25
	v_min_i32_e32 v56, v24, v16
	v_cndmask_b32_e64 v30, 0, 1.0, vcc
	v_cmp_lt_u32_e32 vcc, v28, v14
	v_and_b32_e32 v0, 0xf8, v15
	v_add_u32_e32 v37, 5, v25
	v_cndmask_b32_e64 v28, 0, 1.0, vcc
	v_cmp_lt_u32_e32 vcc, v29, v14
	v_min_i32_e32 v54, v22, v16
	v_add_u32_e32 v23, s61, v23
	v_cndmask_b32_e64 v26, 0, 1.0, vcc
	v_cmp_lt_u32_e32 vcc, v31, v14
	v_lshl_or_b32 v8, v0, 1, v21
	v_add_u32_e32 v39, 6, v25
	v_cndmask_b32_e64 v24, 0, 1.0, vcc
	v_cmp_lt_u32_e32 vcc, v33, v14
	v_lshl_add_u64 v[12:13], s[44:45], 0, v[12:13]
	v_min_i32_e32 v52, v20, v16
	v_cndmask_b32_e64 v22, 0, 1.0, vcc
	v_cmp_lt_u32_e32 vcc, v35, v14
	v_cmp_lt_i32_e64 s[4:5], s40, v23
	v_min_i32_e32 v46, v25, v16
	v_cndmask_b32_e64 v20, 0, 1.0, vcc
	v_cmp_lt_u32_e32 vcc, v37, v14
	v_add_u32_e32 v41, 7, v25
	v_min_i32_e32 v50, v18, v16
	v_lshl_add_u64 v[12:13], v[12:13], 0, v[8:9]
	v_cndmask_b32_e64 v18, 0, 1.0, vcc
	v_cmp_lt_u32_e32 vcc, v39, v14
	s_or_b64 s[34:35], s[4:5], s[34:35]
	v_ashrrev_i32_e32 v45, 31, v44
	v_min_i32_e32 v48, v11, v16
	v_min_i32_e32 v60, v27, v16
	v_ashrrev_i32_e32 v47, 31, v46
	v_min_i32_e32 v64, v29, v16
	v_min_i32_e32 v66, v31, v16
	v_min_i32_e32 v68, v33, v16
	v_min_i32_e32 v70, v35, v16
	v_min_i32_e32 v72, v37, v16
	v_min_i32_e32 v74, v39, v16
	v_min_i32_e32 v76, v41, v16
	v_cndmask_b32_e64 v16, 0, 1.0, vcc
	v_cmp_lt_u32_e32 vcc, v41, v14
	v_add_co_u32_e64 v12, s[4:5], s33, v12
	v_lshlrev_b32_e32 v4, 2, v0
	v_cndmask_b32_e64 v14, 0, 1.0, vcc
	v_lshlrev_b64 v[44:45], 13, v[44:45]
	v_lshlrev_b64 v[46:47], 12, v[46:47]
	v_cmp_lt_i32_e32 vcc, -1, v25
	v_addc_co_u32_e64 v13, s[4:5], 0, v13, s[4:5]
	global_load_dwordx4 v[0:3], v4, s[54:55] offset:3088
	s_nop 0
	global_load_dwordx4 v[4:7], v4, s[54:55] offset:3072
	v_lshl_add_u64 v[78:79], s[44:45], 0, v[44:45]
	v_cndmask_b32_e32 v81, 0, v47, vcc
	v_cndmask_b32_e32 v80, 0, v46, vcc
	global_load_dwordx4 v[44:47], v[12:13], off offset:2048
	v_max_i32_e32 v43, 8, v25
	v_ashrrev_i32_e32 v49, 31, v48
	v_ashrrev_i32_e32 v51, 31, v50
	v_ashrrev_i32_e32 v53, 31, v52
	v_ashrrev_i32_e32 v55, 31, v54
	v_ashrrev_i32_e32 v57, 31, v56
	v_ashrrev_i32_e32 v59, 31, v58
	v_ashrrev_i32_e32 v61, 31, v60
	v_ashrrev_i32_e32 v63, 31, v62
	v_ashrrev_i32_e32 v65, 31, v64
	v_ashrrev_i32_e32 v67, 31, v66
	v_ashrrev_i32_e32 v69, 31, v68
	v_ashrrev_i32_e32 v71, 31, v70
	v_ashrrev_i32_e32 v73, 31, v72
	v_ashrrev_i32_e32 v75, 31, v74
	v_ashrrev_i32_e32 v77, 31, v76
	v_sub_u32_e32 v11, v76, v43
	v_lshlrev_b64 v[48:49], 12, v[48:49]
	v_cmp_lt_i32_e64 s[4:5], 7, v25
	v_lshlrev_b64 v[50:51], 12, v[50:51]
	v_cmp_lt_i32_e64 s[6:7], 6, v25
	v_lshlrev_b64 v[52:53], 12, v[52:53]
	v_cmp_lt_i32_e64 s[8:9], 5, v25
	v_lshlrev_b64 v[54:55], 12, v[54:55]
	v_cmp_lt_i32_e64 s[10:11], 4, v25
	v_lshlrev_b64 v[56:57], 12, v[56:57]
	v_cmp_lt_i32_e64 s[12:13], 3, v25
	v_lshlrev_b64 v[58:59], 12, v[58:59]
	v_cmp_lt_i32_e64 s[14:15], 2, v25
	v_lshlrev_b64 v[60:61], 12, v[60:61]
	v_cmp_lt_i32_e64 s[16:17], 1, v25
	v_lshlrev_b64 v[62:63], 12, v[62:63]
	v_cmp_lt_i32_e64 s[18:19], 0, v25
	v_lshlrev_b64 v[64:65], 12, v[64:65]
	v_cmp_lt_i32_e32 vcc, -2, v25
	v_lshlrev_b64 v[66:67], 12, v[66:67]
	v_cmp_lt_i32_e64 s[20:21], -3, v25
	v_lshlrev_b64 v[68:69], 12, v[68:69]
	v_cmp_lt_i32_e64 s[22:23], -4, v25
	v_lshlrev_b64 v[70:71], 12, v[70:71]
	v_cmp_lt_i32_e64 s[24:25], -5, v25
	v_lshlrev_b64 v[72:73], 12, v[72:73]
	v_cmp_lt_i32_e64 s[26:27], -6, v25
	v_lshlrev_b64 v[74:75], 12, v[74:75]
	v_cmp_lt_i32_e64 s[28:29], -7, v25
	v_lshlrev_b64 v[76:77], 12, v[76:77]
	v_cmp_lt_i32_e64 s[30:31], -8, v25
	v_lshl_add_u64 v[78:79], v[78:79], 0, s[36:37]
	v_cndmask_b32_e64 v49, 0, v49, s[4:5]
	v_cndmask_b32_e64 v48, 0, v48, s[4:5]
	v_cndmask_b32_e64 v51, 0, v51, s[6:7]
	v_cndmask_b32_e64 v50, 0, v50, s[6:7]
	v_cndmask_b32_e64 v53, 0, v53, s[8:9]
	v_cndmask_b32_e64 v52, 0, v52, s[8:9]
	v_cndmask_b32_e64 v55, 0, v55, s[10:11]
	v_cndmask_b32_e64 v54, 0, v54, s[10:11]
	v_cndmask_b32_e64 v57, 0, v57, s[12:13]
	v_cndmask_b32_e64 v56, 0, v56, s[12:13]
	v_cndmask_b32_e64 v59, 0, v59, s[14:15]
	v_cndmask_b32_e64 v58, 0, v58, s[14:15]
	v_cndmask_b32_e64 v61, 0, v61, s[16:17]
	v_cndmask_b32_e64 v60, 0, v60, s[16:17]
	v_cndmask_b32_e64 v63, 0, v63, s[18:19]
	v_cndmask_b32_e64 v62, 0, v62, s[18:19]
	v_cndmask_b32_e32 v65, 0, v65, vcc
	v_cndmask_b32_e32 v64, 0, v64, vcc
	v_cndmask_b32_e64 v67, 0, v67, s[20:21]
	v_cndmask_b32_e64 v66, 0, v66, s[20:21]
	v_cndmask_b32_e64 v69, 0, v69, s[22:23]
	v_cndmask_b32_e64 v68, 0, v68, s[22:23]
	v_cndmask_b32_e64 v71, 0, v71, s[24:25]
	v_cndmask_b32_e64 v70, 0, v70, s[24:25]
	v_cndmask_b32_e64 v73, 0, v73, s[26:27]
	v_cndmask_b32_e64 v72, 0, v72, s[26:27]
	v_cndmask_b32_e64 v75, 0, v75, s[28:29]
	v_cndmask_b32_e64 v74, 0, v74, s[28:29]
	v_cndmask_b32_e64 v77, 0, v77, s[30:31]
	v_cndmask_b32_e64 v76, 0, v76, s[30:31]
	v_lshl_add_u64 v[48:49], v[48:49], 1, v[78:79]
	v_lshl_add_u64 v[50:51], v[50:51], 1, v[78:79]
	v_lshl_add_u64 v[52:53], v[52:53], 1, v[78:79]
	v_lshl_add_u64 v[54:55], v[54:55], 1, v[78:79]
	v_lshl_add_u64 v[56:57], v[56:57], 1, v[78:79]
	v_lshl_add_u64 v[58:59], v[58:59], 1, v[78:79]
	v_lshl_add_u64 v[60:61], v[60:61], 1, v[78:79]
	v_lshl_add_u64 v[62:63], v[62:63], 1, v[78:79]
	v_lshl_add_u64 v[80:81], v[80:81], 1, v[78:79]
	v_lshl_add_u64 v[64:65], v[64:65], 1, v[78:79]
	v_lshl_add_u64 v[66:67], v[66:67], 1, v[78:79]
	v_lshl_add_u64 v[68:69], v[68:69], 1, v[78:79]
	v_lshl_add_u64 v[70:71], v[70:71], 1, v[78:79]
	v_lshl_add_u64 v[72:73], v[72:73], 1, v[78:79]
	v_lshl_add_u64 v[74:75], v[74:75], 1, v[78:79]
	v_lshl_add_u64 v[76:77], v[76:77], 1, v[78:79]
	v_lshl_add_u64 v[48:49], v[48:49], 0, v[8:9]
	v_lshl_add_u64 v[78:79], v[50:51], 0, v[8:9]
	v_lshl_add_u64 v[82:83], v[52:53], 0, v[8:9]
	v_lshl_add_u64 v[84:85], v[54:55], 0, v[8:9]
	v_lshl_add_u64 v[86:87], v[56:57], 0, v[8:9]
	v_lshl_add_u64 v[88:89], v[58:59], 0, v[8:9]
	v_lshl_add_u64 v[90:91], v[60:61], 0, v[8:9]
	v_lshl_add_u64 v[92:93], v[62:63], 0, v[8:9]
	v_lshl_add_u64 v[80:81], v[80:81], 0, v[8:9]
	v_lshl_add_u64 v[94:95], v[64:65], 0, v[8:9]
	v_lshl_add_u64 v[96:97], v[66:67], 0, v[8:9]
	v_lshl_add_u64 v[98:99], v[68:69], 0, v[8:9]
	v_lshl_add_u64 v[100:101], v[70:71], 0, v[8:9]
	v_lshl_add_u64 v[102:103], v[72:73], 0, v[8:9]
	v_lshl_add_u64 v[104:105], v[74:75], 0, v[8:9]
	v_lshl_add_u64 v[108:109], v[76:77], 0, v[8:9]
	global_load_dwordx4 v[48:51], v[48:49], off
	s_nop 0
	global_load_dwordx4 v[52:55], v[78:79], off
	global_load_dwordx4 v[56:59], v[82:83], off
	global_load_dwordx4 v[60:63], v[84:85], off
	global_load_dwordx4 v[64:67], v[86:87], off
	global_load_dwordx4 v[68:71], v[88:89], off
	global_load_dwordx4 v[72:75], v[90:91], off
	global_load_dwordx4 v[76:79], v[92:93], off
	s_nop 0
	global_load_dwordx4 v[80:83], v[80:81], off
	s_nop 0
	global_load_dwordx4 v[84:87], v[94:95], off
	global_load_dwordx4 v[88:91], v[96:97], off
	s_nop 0
	global_load_dwordx4 v[92:95], v[98:99], off
	s_nop 0
	global_load_dwordx4 v[96:99], v[100:101], off
	s_nop 0
	global_load_dwordx4 v[100:103], v[102:103], off
	s_nop 0
	global_load_dwordx4 v[104:107], v[104:105], off
	s_nop 0
	global_load_dwordx4 v[108:111], v[108:109], off
	v_add_u32_e32 v11, 9, v11
	v_cvt_f32_i32_e32 v11, v11
	s_waitcnt vmcnt(17)
	v_mov_b32_e32 v112, v4
	v_mov_b32_e32 v113, v6
	v_mov_b32_e32 v6, v5
	v_div_scale_f32 v8, s[4:5], v11, v11, 1.0
	v_rcp_f32_e32 v27, v8
	v_div_scale_f32 v25, vcc, 1.0, v11, 1.0
	v_mov_b32_e32 v4, v0
	v_fma_f32 v29, -v8, v27, 1.0
	v_fmac_f32_e32 v27, v29, v27
	v_mul_f32_e32 v29, v25, v27
	v_fma_f32 v31, -v8, v29, v25
	v_fmac_f32_e32 v29, v31, v27
	v_fma_f32 v8, -v8, v29, v25
	v_div_fmas_f32 v8, v8, v27, v29
	v_mov_b32_e32 v5, v2
	v_mov_b32_e32 v2, v1
	s_waitcnt vmcnt(16)
	v_lshlrev_b32_e32 v1, 16, v45
	v_lshlrev_b32_e32 v0, 16, v44
	v_div_fixup_f32 v8, v8, v11, 1.0
	v_lshlrev_b32_e32 v115, 16, v47
	v_and_b32_e32 v47, 0xffff0000, v47
	v_mul_f32_e32 v11, 0xbfb8aa3b, v0
	v_mul_f32_e32 v27, 0xbfb8aa3b, v1
	v_mul_f32_e32 v37, 0xbfb8aa3b, v47
	v_exp_f32_e32 v11, v11
	v_exp_f32_e32 v27, v27
	v_lshlrev_b32_e32 v114, 16, v46
	v_and_b32_e32 v46, 0xffff0000, v46
	v_mul_f32_e32 v35, 0xbfb8aa3b, v115
	v_exp_f32_e32 v37, v37
	v_mul_f32_e32 v33, 0xbfb8aa3b, v46
	v_exp_f32_e32 v35, v35
	v_and_b32_e32 v45, 0xffff0000, v45
	v_mul_f32_e32 v31, 0xbfb8aa3b, v114
	v_exp_f32_e32 v33, v33
	v_mul_f32_e32 v29, 0xbfb8aa3b, v45
	v_exp_f32_e32 v31, v31
	v_add_f32_e32 v11, 1.0, v11
	v_add_f32_e32 v27, 1.0, v27
	v_exp_f32_e32 v29, v29
	v_add_f32_e32 v37, 1.0, v37
	v_and_b32_e32 v44, 0xffff0000, v44
	v_add_f32_e32 v35, 1.0, v35
	v_mul_f32_e32 v25, 0xbfb8aa3b, v44
	v_add_f32_e32 v33, 1.0, v33
	v_exp_f32_e32 v25, v25
	v_add_f32_e32 v31, 1.0, v31
	v_add_f32_e32 v29, 1.0, v29
	v_add_u32_e32 v15, s0, v15
	v_add_f32_e32 v25, 1.0, v25
	s_waitcnt vmcnt(15)
	v_lshlrev_b32_e32 v117, 16, v49
	v_lshlrev_b32_e32 v116, 16, v48
	v_and_b32_e32 v49, 0xffff0000, v49
	v_and_b32_e32 v48, 0xffff0000, v48
	v_lshlrev_b32_e32 v123, 16, v51
	v_lshlrev_b32_e32 v122, 16, v50
	v_and_b32_e32 v51, 0xffff0000, v51
	v_and_b32_e32 v50, 0xffff0000, v50
	s_waitcnt vmcnt(14)
	v_lshlrev_b32_e32 v119, 16, v53
	v_lshlrev_b32_e32 v118, 16, v52
	v_and_b32_e32 v53, 0xffff0000, v53
	v_and_b32_e32 v52, 0xffff0000, v52
	v_lshlrev_b32_e32 v125, 16, v55
	v_lshlrev_b32_e32 v124, 16, v54
	v_and_b32_e32 v55, 0xffff0000, v55
	v_and_b32_e32 v54, 0xffff0000, v54
	v_pk_fma_f32 v[116:117], v[42:43], v[116:117], 0 op_sel_hi:[0,1,0]
	v_pk_fma_f32 v[48:49], v[42:43], v[48:49], 0 op_sel_hi:[0,1,0]
	v_pk_fma_f32 v[122:123], v[42:43], v[122:123], 0 op_sel_hi:[0,1,0]
	v_pk_fma_f32 v[42:43], v[42:43], v[50:51], 0 op_sel_hi:[0,1,0]
	s_waitcnt vmcnt(13)
	v_lshlrev_b32_e32 v121, 16, v57
	v_lshlrev_b32_e32 v120, 16, v56
	v_and_b32_e32 v57, 0xffff0000, v57
	v_and_b32_e32 v56, 0xffff0000, v56
	v_lshlrev_b32_e32 v127, 16, v59
	v_lshlrev_b32_e32 v126, 16, v58
	v_and_b32_e32 v59, 0xffff0000, v59
	v_and_b32_e32 v58, 0xffff0000, v58
	v_pk_fma_f32 v[50:51], v[40:41], v[118:119], v[116:117] op_sel_hi:[0,1,1]
	v_pk_fma_f32 v[48:49], v[40:41], v[52:53], v[48:49] op_sel_hi:[0,1,1]
	v_pk_fma_f32 v[52:53], v[40:41], v[124:125], v[122:123] op_sel_hi:[0,1,1]
	v_pk_fma_f32 v[40:41], v[40:41], v[54:55], v[42:43] op_sel_hi:[0,1,1]
	s_waitcnt vmcnt(12)
	v_lshlrev_b32_e32 v129, 16, v61
	v_lshlrev_b32_e32 v128, 16, v60
	v_and_b32_e32 v61, 0xffff0000, v61
	v_and_b32_e32 v60, 0xffff0000, v60
	v_lshlrev_b32_e32 v131, 16, v63
	v_lshlrev_b32_e32 v130, 16, v62
	v_pk_fma_f32 v[42:43], v[38:39], v[120:121], v[50:51] op_sel_hi:[0,1,1]
	v_pk_fma_f32 v[48:49], v[38:39], v[56:57], v[48:49] op_sel_hi:[0,1,1]
	v_pk_fma_f32 v[50:51], v[38:39], v[126:127], v[52:53] op_sel_hi:[0,1,1]
	v_pk_fma_f32 v[38:39], v[38:39], v[58:59], v[40:41] op_sel_hi:[0,1,1]
	v_rcp_f32_e32 v40, v11
	v_rcp_f32_e32 v41, v27
	v_and_b32_e32 v63, 0xffff0000, v63
	v_and_b32_e32 v62, 0xffff0000, v62
	s_waitcnt vmcnt(11)
	v_lshlrev_b32_e32 v133, 16, v65
	v_lshlrev_b32_e32 v132, 16, v64
	v_and_b32_e32 v65, 0xffff0000, v65
	v_and_b32_e32 v64, 0xffff0000, v64
	v_lshlrev_b32_e32 v135, 16, v67
	v_lshlrev_b32_e32 v134, 16, v66
	v_pk_fma_f32 v[42:43], v[36:37], v[128:129], v[42:43] op_sel_hi:[0,1,1]
	v_pk_fma_f32 v[48:49], v[36:37], v[60:61], v[48:49] op_sel_hi:[0,1,1]
	v_pk_fma_f32 v[50:51], v[36:37], v[130:131], v[50:51] op_sel_hi:[0,1,1]
	v_and_b32_e32 v67, 0xffff0000, v67
	v_and_b32_e32 v66, 0xffff0000, v66
	s_waitcnt vmcnt(10)
	v_lshlrev_b32_e32 v136, 16, v68
	v_and_b32_e32 v68, 0xffff0000, v68
	v_lshlrev_b32_e32 v137, 16, v69
	v_and_b32_e32 v69, 0xffff0000, v69
	v_lshlrev_b32_e32 v138, 16, v70
	v_lshlrev_b32_e32 v139, 16, v71
	v_rcp_f32_e32 v57, v37
	v_pk_fma_f32 v[36:37], v[36:37], v[62:63], v[38:39] op_sel_hi:[0,1,1]
	v_pk_fma_f32 v[38:39], v[34:35], v[132:133], v[42:43] op_sel_hi:[0,1,1]
	v_pk_fma_f32 v[42:43], v[34:35], v[64:65], v[48:49] op_sel_hi:[0,1,1]
	v_pk_fma_f32 v[48:49], v[34:35], v[134:135], v[50:51] op_sel_hi:[0,1,1]
	v_and_b32_e32 v70, 0xffff0000, v70
	v_and_b32_e32 v71, 0xffff0000, v71
	s_waitcnt vmcnt(9)
	v_lshlrev_b32_e32 v151, 16, v73
	v_lshlrev_b32_e32 v150, 16, v72
	v_and_b32_e32 v73, 0xffff0000, v73
	v_and_b32_e32 v72, 0xffff0000, v72
	v_lshlrev_b32_e32 v167, 16, v75
	v_lshlrev_b32_e32 v166, 16, v74
	v_rcp_f32_e32 v55, v35
	v_pk_fma_f32 v[34:35], v[34:35], v[66:67], v[36:37] op_sel_hi:[0,1,1]
	v_pk_fma_f32 v[36:37], v[32:33], v[136:137], v[38:39] op_sel_hi:[0,1,1]
	v_pk_fma_f32 v[38:39], v[32:33], v[68:69], v[42:43] op_sel_hi:[0,1,1]
	v_pk_fma_f32 v[42:43], v[32:33], v[138:139], v[48:49] op_sel_hi:[0,1,1]
	s_waitcnt vmcnt(8)
	v_lshlrev_b32_e32 v153, 16, v77
	v_lshlrev_b32_e32 v152, 16, v76
	v_and_b32_e32 v77, 0xffff0000, v77
	v_and_b32_e32 v76, 0xffff0000, v76
	v_lshlrev_b32_e32 v187, 16, v79
	v_lshlrev_b32_e32 v186, 16, v78
	v_and_b32_e32 v75, 0xffff0000, v75
	v_and_b32_e32 v74, 0xffff0000, v74
	v_rcp_f32_e32 v56, v33
	v_pk_fma_f32 v[32:33], v[32:33], v[70:71], v[34:35] op_sel_hi:[0,1,1]
	v_pk_fma_f32 v[34:35], v[30:31], v[150:151], v[36:37] op_sel_hi:[0,1,1]
	v_pk_fma_f32 v[36:37], v[30:31], v[72:73], v[38:39] op_sel_hi:[0,1,1]
	v_pk_mul_f32 v[0:1], v[40:41], v[0:1]
	v_pk_fma_f32 v[40:41], v[30:31], v[166:167], v[42:43] op_sel_hi:[0,1,1]
	s_waitcnt vmcnt(7)
	v_lshlrev_b32_e32 v149, 16, v81
	v_lshlrev_b32_e32 v148, 16, v80
	v_and_b32_e32 v81, 0xffff0000, v81
	v_and_b32_e32 v80, 0xffff0000, v80
	v_lshlrev_b32_e32 v165, 16, v83
	v_lshlrev_b32_e32 v164, 16, v82
	v_and_b32_e32 v79, 0xffff0000, v79
	v_and_b32_e32 v78, 0xffff0000, v78
	v_rcp_f32_e32 v54, v31
	v_pk_fma_f32 v[30:31], v[30:31], v[74:75], v[32:33] op_sel_hi:[0,1,1]
	v_pk_fma_f32 v[34:35], v[28:29], v[152:153], v[34:35] op_sel_hi:[0,1,1]
	v_pk_fma_f32 v[36:37], v[28:29], v[76:77], v[36:37] op_sel_hi:[0,1,1]
	v_pk_fma_f32 v[40:41], v[28:29], v[186:187], v[40:41] op_sel_hi:[0,1,1]
	s_waitcnt vmcnt(6)
	v_lshlrev_b32_e32 v155, 16, v85
	v_lshlrev_b32_e32 v154, 16, v84
	v_and_b32_e32 v85, 0xffff0000, v85
	v_and_b32_e32 v84, 0xffff0000, v84
	v_and_b32_e32 v83, 0xffff0000, v83
	v_and_b32_e32 v82, 0xffff0000, v82
	v_lshlrev_b32_e32 v189, 16, v87
	v_lshlrev_b32_e32 v188, 16, v86
	v_rcp_f32_e32 v53, v29
	v_pk_fma_f32 v[28:29], v[28:29], v[78:79], v[30:31] op_sel_hi:[0,1,1]
	v_pk_fma_f32 v[30:31], v[10:11], v[148:149], v[34:35] op_sel_hi:[0,1,1]
	v_pk_fma_f32 v[34:35], v[10:11], v[80:81], v[36:37] op_sel_hi:[0,1,1]
	v_pk_fma_f32 v[36:37], v[10:11], v[164:165], v[40:41] op_sel_hi:[0,1,1]
	s_waitcnt vmcnt(5)
	v_lshlrev_b32_e32 v157, 16, v89
	v_lshlrev_b32_e32 v156, 16, v88
	v_and_b32_e32 v89, 0xffff0000, v89
	v_and_b32_e32 v88, 0xffff0000, v88
	v_lshlrev_b32_e32 v191, 16, v91
	v_lshlrev_b32_e32 v190, 16, v90
	v_and_b32_e32 v87, 0xffff0000, v87
	v_and_b32_e32 v86, 0xffff0000, v86
	v_pk_fma_f32 v[10:11], v[10:11], v[82:83], v[28:29] op_sel_hi:[0,1,1]
	v_pk_fma_f32 v[28:29], v[26:27], v[154:155], v[30:31] op_sel_hi:[0,1,1]
	v_pk_fma_f32 v[30:31], v[26:27], v[84:85], v[34:35] op_sel_hi:[0,1,1]
	v_pk_fma_f32 v[34:35], v[26:27], v[188:189], v[36:37] op_sel_hi:[0,1,1]
	s_waitcnt vmcnt(4)
	v_lshlrev_b32_e32 v159, 16, v93
	v_lshlrev_b32_e32 v158, 16, v92
	v_and_b32_e32 v93, 0xffff0000, v93
	v_and_b32_e32 v92, 0xffff0000, v92
	v_lshlrev_b32_e32 v207, 16, v95
	v_lshlrev_b32_e32 v206, 16, v94
	v_and_b32_e32 v91, 0xffff0000, v91
	v_and_b32_e32 v90, 0xffff0000, v90
	v_pk_fma_f32 v[10:11], v[26:27], v[86:87], v[10:11] op_sel_hi:[0,1,1]
	v_pk_fma_f32 v[26:27], v[24:25], v[156:157], v[28:29] op_sel_hi:[0,1,1]
	v_pk_fma_f32 v[28:29], v[24:25], v[88:89], v[30:31] op_sel_hi:[0,1,1]
	v_pk_fma_f32 v[30:31], v[24:25], v[190:191], v[34:35] op_sel_hi:[0,1,1]
	s_waitcnt vmcnt(3)
	v_lshlrev_b32_e32 v161, 16, v97
	v_lshlrev_b32_e32 v160, 16, v96
	v_lshlrev_b32_e32 v209, 16, v99
	v_lshlrev_b32_e32 v208, 16, v98
	v_and_b32_e32 v95, 0xffff0000, v95
	v_and_b32_e32 v94, 0xffff0000, v94
	v_rcp_f32_e32 v52, v25
	v_pk_fma_f32 v[10:11], v[24:25], v[90:91], v[10:11] op_sel_hi:[0,1,1]
	v_pk_fma_f32 v[24:25], v[22:23], v[158:159], v[26:27] op_sel_hi:[0,1,1]
	v_pk_fma_f32 v[26:27], v[22:23], v[92:93], v[28:29] op_sel_hi:[0,1,1]
	v_pk_fma_f32 v[28:29], v[22:23], v[206:207], v[30:31] op_sel_hi:[0,1,1]
	s_waitcnt vmcnt(2)
	v_lshlrev_b32_e32 v163, 16, v101
	v_lshlrev_b32_e32 v162, 16, v100
	v_and_b32_e32 v97, 0xffff0000, v97
	v_and_b32_e32 v96, 0xffff0000, v96
	v_lshlrev_b32_e32 v211, 16, v103
	v_lshlrev_b32_e32 v210, 16, v102
	v_and_b32_e32 v99, 0xffff0000, v99
	v_and_b32_e32 v98, 0xffff0000, v98
	v_pk_fma_f32 v[10:11], v[22:23], v[94:95], v[10:11] op_sel_hi:[0,1,1]
	v_pk_fma_f32 v[24:25], v[20:21], v[160:161], v[24:25] op_sel_hi:[0,1,1]
	v_pk_fma_f32 v[28:29], v[20:21], v[208:209], v[28:29] op_sel_hi:[0,1,1]
	s_waitcnt vmcnt(1)
	v_lshlrev_b32_e32 v141, 16, v105
	v_lshlrev_b32_e32 v140, 16, v104
	v_lshlrev_b32_e32 v143, 16, v107
	v_lshlrev_b32_e32 v142, 16, v106
	v_and_b32_e32 v101, 0xffff0000, v101
	v_and_b32_e32 v100, 0xffff0000, v100
	v_and_b32_e32 v103, 0xffff0000, v103
	v_and_b32_e32 v102, 0xffff0000, v102
	v_pk_fma_f32 v[26:27], v[20:21], v[96:97], v[26:27] op_sel_hi:[0,1,1]
	v_pk_fma_f32 v[10:11], v[20:21], v[98:99], v[10:11] op_sel_hi:[0,1,1]
	v_pk_fma_f32 v[24:25], v[18:19], v[162:163], v[24:25] op_sel_hi:[0,1,1]
	v_pk_fma_f32 v[28:29], v[18:19], v[210:211], v[28:29] op_sel_hi:[0,1,1]
	v_and_b32_e32 v105, 0xffff0000, v105
	v_and_b32_e32 v104, 0xffff0000, v104
	v_and_b32_e32 v107, 0xffff0000, v107
	v_and_b32_e32 v106, 0xffff0000, v106
	s_waitcnt vmcnt(0)
	v_lshlrev_b32_e32 v145, 16, v109
	v_lshlrev_b32_e32 v144, 16, v108
	v_lshlrev_b32_e32 v147, 16, v111
	v_lshlrev_b32_e32 v146, 16, v110
	v_pk_fma_f32 v[26:27], v[18:19], v[100:101], v[26:27] op_sel_hi:[0,1,1]
	v_pk_fma_f32 v[10:11], v[18:19], v[102:103], v[10:11] op_sel_hi:[0,1,1]
	v_pk_fma_f32 v[24:25], v[16:17], v[140:141], v[24:25] op_sel_hi:[0,1,1]
	v_pk_fma_f32 v[28:29], v[16:17], v[142:143], v[28:29] op_sel_hi:[0,1,1]
	v_and_b32_e32 v109, 0xffff0000, v109
	v_and_b32_e32 v108, 0xffff0000, v108
	v_and_b32_e32 v111, 0xffff0000, v111
	v_and_b32_e32 v110, 0xffff0000, v110
	v_pk_fma_f32 v[26:27], v[16:17], v[104:105], v[26:27] op_sel_hi:[0,1,1]
	v_pk_fma_f32 v[10:11], v[16:17], v[106:107], v[10:11] op_sel_hi:[0,1,1]
	v_pk_fma_f32 v[24:25], v[14:15], v[144:145], v[24:25] op_sel_hi:[0,1,1]
	v_pk_fma_f32 v[28:29], v[14:15], v[146:147], v[28:29] op_sel_hi:[0,1,1]
	v_pk_fma_f32 v[26:27], v[14:15], v[108:109], v[26:27] op_sel_hi:[0,1,1]
	v_pk_fma_f32 v[10:11], v[14:15], v[110:111], v[10:11] op_sel_hi:[0,1,1]
	v_pk_fma_f32 v[24:25], v[8:9], v[24:25], v[148:149] op_sel_hi:[0,1,1] neg_lo:[0,0,1] neg_hi:[0,0,1]
	v_pk_fma_f32 v[28:29], v[8:9], v[28:29], v[164:165] op_sel_hi:[0,1,1] neg_lo:[0,0,1] neg_hi:[0,0,1]
	v_pk_mul_f32 v[32:33], v[54:55], v[114:115]
	v_pk_fma_f32 v[26:27], v[8:9], v[26:27], v[80:81] op_sel_hi:[0,1,1] neg_lo:[0,0,1] neg_hi:[0,0,1]
	v_pk_fma_f32 v[10:11], v[8:9], v[10:11], v[82:83] op_sel_hi:[0,1,1] neg_lo:[0,0,1] neg_hi:[0,0,1]
	v_pk_mul_f32 v[24:25], v[112:113], v[24:25]
	v_pk_mul_f32 v[4:5], v[4:5], v[28:29]
	v_pk_mul_f32 v[38:39], v[52:53], v[44:45]
	v_pk_mul_f32 v[42:43], v[56:57], v[46:47]
	v_pk_mul_f32 v[6:7], v[6:7], v[26:27]
	v_pk_mul_f32 v[2:3], v[2:3], v[10:11]
	v_pk_mul_f32 v[0:1], v[0:1], v[24:25]
	v_pk_mul_f32 v[4:5], v[32:33], v[4:5]
	v_pk_mul_f32 v[6:7], v[38:39], v[6:7]
	v_pk_mul_f32 v[2:3], v[42:43], v[2:3]
	v_bfe_u32 v16, v0, 16, 1
	v_bfe_u32 v18, v1, 16, 1
	v_bfe_u32 v20, v4, 16, 1
	v_bfe_u32 v22, v5, 16, 1
	v_bfe_u32 v8, v3, 16, 1
	v_bfe_u32 v10, v2, 16, 1
	v_bfe_u32 v11, v7, 16, 1
	v_bfe_u32 v14, v6, 16, 1
	v_add3_u32 v5, v5, v22, s39
	v_add3_u32 v4, v4, v20, s39
	v_add3_u32 v1, v1, v18, s39
	v_add3_u32 v0, v0, v16, s39
	v_add3_u32 v6, v6, v14, s39
	v_add3_u32 v7, v7, v11, s39
	v_add3_u32 v2, v2, v10, s39
	v_add3_u32 v3, v3, v8, s39
	v_lshrrev_b32_e32 v0, 16, v0
	v_lshrrev_b32_e32 v1, 16, v1
	v_lshrrev_b32_e32 v4, 16, v4
	v_lshrrev_b32_e32 v5, 16, v5
	v_and_or_b32 v3, v3, s38, v5
	v_and_or_b32 v2, v2, s38, v4
	v_and_or_b32 v1, v7, s38, v1
	v_and_or_b32 v0, v6, s38, v0
	global_store_dwordx4 v[12:13], v[0:3], off offset:2048
	s_andn2_b64 exec, exec, s[34:35]
	s_cbranch_execnz .LBB0_521

; __global__ void __launch_bounds__(512, 2) fwd_megakernel(Args a) {
;     ...
;     for (int idx0 = gt; idx0 < MT * 256; idx0 += 2 * NGT) {
;         u32x4 z0[2], z1[2], z2[2], wg[2]; f32x4 cw[2][3][2];
; #pragma unroll
;         for (int u = 0; u < 2; ++u) { const int idx = idx0 + u * NGT; if (idx < MT * 256) {
;             const int row = idx >> 8, c0 = (idx & 255) * 8;
;             int t, S; if (row < MP) { t = row & 2047; S = 2048; } else { t = row - MP; S = 16384; }
;             const bf16_t* zp = RB + (size_t)row * LDB + c0;
;             z1[u] = *(const u32x4*)zp;
;             const u32x4 za = *(const u32x4*)(t > 0 ? zp - LDB : zp), zb = *(const u32x4*)(t < S - 1 ? zp + LDB : zp);
;             const unsigned ma = t > 0 ? 0xffffffffu : 0u, mb = t < S - 1 ? 0xffffffffu : 0u;
;             z0[u] = (u32x4){za.x & ma, za.y & ma, za.z & ma, za.w & ma}; z2[u] = (u32x4){zb.x & mb, zb.y & mb, zb.z & mb, zb.w & mb};
;             wg[u] = *(const u32x4*)(zp + 2048);
; #pragma unroll
;             for (int k = 0; k < 3; ++k) { cw[u][k][0] = *(const f32x4*)(conv_w + k * 2048 + c0); cw[u][k][1] = *(const f32x4*)(conv_w + k * 2048 + c0 + 4); } } }
.LBB0_918:
	s_or_b64 exec, exec, s[2:3]
	s_mov_b32 s22, 0x600000
	v_cmp_gt_i32_e32 vcc, s22, v176
	s_waitcnt lgkmcnt(0)
	s_barrier
	s_and_saveexec_b64 s[2:3], vcc
	v_readlane_b32 s62, v255, 9
	s_nop 3
	s_cmp_eq_u32 s62, 0x100
	s_cbranch_scc0 .Lp8_old
	v_readlane_b32 s54, v255, 44
	v_readlane_b32 s55, v255, 45
	v_readlane_b32 s60, v255, 0
	v_readlane_b32 s61, v255, 1
	s_nop 3
	s_add_u32 s56, s54, 0x1000
	s_addc_u32 s57, s55, 0
	s_add_u32 s58, s94, 0x2000
	s_addc_u32 s59, s95, 0
	v_readlane_b32 s64, v255, 13
	s_movk_i32 s63, 2
	v_lshrrev_b32_e32 v128, 8, v168
	s_mul_i32 s64, s64, 0x60
	v_add_u32_e32 v128, s64, v128
	v_and_b32_e32 v135, 0xff, v176
	v_lshlrev_b32_e32 v135, 4, v135
	v_lshlrev_b32_e32 v134, 1, v135
	v_mov_b32_e32 v136, 0x2000
	v_mov_b32_e32 v137, 0x7ff
	v_mov_b32_e32 v138, 0x3fff
	v_add_u32_e32 v131, 0, v134
	global_load_dwordx4 v[4:7], v131, s[60:61]
	global_load_dwordx4 v[8:11], v131, s[60:61] offset:16
	v_add_u32_e32 v131, 8192, v134
	global_load_dwordx4 v[12:15], v131, s[60:61]
	global_load_dwordx4 v[16:19], v131, s[60:61] offset:16
	v_add_u32_e32 v131, 16384, v134
	global_load_dwordx4 v[20:23], v131, s[60:61]
	global_load_dwordx4 v[24:27], v131, s[60:61] offset:16
	v_cmp_gt_u32_e32 vcc, 0x2000, v128
	v_and_b32_e32 v129, 0x7ff, v128
	v_subrev_u32_e32 v134, 0x2000, v128
	v_lshl_add_u32 v131, v128, 13, v135
	v_cndmask_b32_e32 v129, v134, v129, vcc
	v_cndmask_b32_e32 v130, v138, v137, vcc
	s_nop 0
	v_cmp_lt_u32_e32 vcc, 0, v129
	v_mul_u32_u24_e32 v134, 0x3000, v128
	v_add_u32_e32 v62, v134, v135
	v_cndmask_b32_e64 v60, 0, -1, vcc
	v_cndmask_b32_e32 v134, 0, v136, vcc
	v_sub_u32_e32 v132, v131, v134
	v_cmp_lt_u32_e32 vcc, v129, v130
	global_load_dwordx4 v[28:31], v131, s[54:55]
	global_load_dwordx4 v[32:35], v132, s[54:55]
	v_cndmask_b32_e64 v61, 0, -1, vcc
	v_cndmask_b32_e32 v134, 0, v136, vcc
	v_add_u32_e32 v133, v131, v134
	global_load_dwordx4 v[36:39], v133, s[54:55]
	global_load_dwordx4 v[40:43], v131, s[56:57]
	v_add_u32_e32 v128, s63, v128
	v_cmp_gt_u32_e32 vcc, 0x2000, v128
	v_and_b32_e32 v129, 0x7ff, v128
	v_subrev_u32_e32 v134, 0x2000, v128
	v_lshl_add_u32 v131, v128, 13, v135
	v_cndmask_b32_e32 v129, v134, v129, vcc
	v_cndmask_b32_e32 v130, v138, v137, vcc
	s_nop 0
	v_cmp_lt_u32_e32 vcc, 0, v129
	v_mul_u32_u24_e32 v134, 0x3000, v128
	v_add_u32_e32 v65, v134, v135
	v_cndmask_b32_e64 v63, 0, -1, vcc
	v_cndmask_b32_e32 v134, 0, v136, vcc
	v_sub_u32_e32 v132, v131, v134
	v_cmp_lt_u32_e32 vcc, v129, v130
	global_load_dwordx4 v[44:47], v131, s[54:55]
	global_load_dwordx4 v[48:51], v132, s[54:55]
	v_cndmask_b32_e64 v64, 0, -1, vcc
	v_cndmask_b32_e32 v134, 0, v136, vcc
	v_add_u32_e32 v133, v131, v134
	global_load_dwordx4 v[52:55], v133, s[54:55]
	global_load_dwordx4 v[56:59], v131, s[56:57]
	v_add_u32_e32 v128, s63, v128
	s_mov_b32 s62, 23
.Lp8_loop:
	v_cmp_gt_u32_e32 vcc, 0x2000, v128
	v_and_b32_e32 v129, 0x7ff, v128
	v_subrev_u32_e32 v134, 0x2000, v128
	v_lshl_add_u32 v131, v128, 13, v135
	v_cndmask_b32_e32 v129, v134, v129, vcc
	v_cndmask_b32_e32 v130, v138, v137, vcc
	s_nop 0
	v_cmp_lt_u32_e32 vcc, 0, v129
	v_mul_u32_u24_e32 v134, 0x3000, v128
	v_add_u32_e32 v114, v134, v135
	v_cndmask_b32_e64 v112, 0, -1, vcc
	v_cndmask_b32_e32 v134, 0, v136, vcc
	v_sub_u32_e32 v132, v131, v134
	v_cmp_lt_u32_e32 vcc, v129, v130
	global_load_dwordx4 v[80:83], v131, s[54:55]
	global_load_dwordx4 v[84:87], v132, s[54:55]
	v_cndmask_b32_e64 v113, 0, -1, vcc
	v_cndmask_b32_e32 v134, 0, v136, vcc
	v_add_u32_e32 v133, v131, v134
	global_load_dwordx4 v[88:91], v133, s[54:55]
	global_load_dwordx4 v[92:95], v131, s[56:57]
	v_add_u32_e32 v128, s63, v128
	v_cmp_gt_u32_e32 vcc, 0x2000, v128
	v_and_b32_e32 v129, 0x7ff, v128
	v_subrev_u32_e32 v134, 0x2000, v128
	v_lshl_add_u32 v131, v128, 13, v135
	v_cndmask_b32_e32 v129, v134, v129, vcc
	v_cndmask_b32_e32 v130, v138, v137, vcc
	s_nop 0
	v_cmp_lt_u32_e32 vcc, 0, v129
	v_mul_u32_u24_e32 v134, 0x3000, v128
	v_add_u32_e32 v117, v134, v135
	v_cndmask_b32_e64 v115, 0, -1, vcc
	v_cndmask_b32_e32 v134, 0, v136, vcc
	v_sub_u32_e32 v132, v131, v134
	v_cmp_lt_u32_e32 vcc, v129, v130
	global_load_dwordx4 v[96:99], v131, s[54:55]
	global_load_dwordx4 v[100:103], v132, s[54:55]
	v_cndmask_b32_e64 v116, 0, -1, vcc
	v_cndmask_b32_e32 v134, 0, v136, vcc
	v_add_u32_e32 v133, v131, v134
	global_load_dwordx4 v[104:107], v133, s[54:55]
	global_load_dwordx4 v[108:111], v131, s[56:57]
	v_add_u32_e32 v128, s63, v128
	s_waitcnt vmcnt(8)
; __device__ __forceinline__ unsigned pk2(float lo, float hi) { return f2bf(lo) | (f2bf(hi) << 16); }
; __global__ void __launch_bounds__(512, 2) fwd_megakernel(Args a) {
;     ...
;         for (int u = 0; u < 2; ++u) { const int idx = idx0 + u * NGT; if (idx < MT * 256) {
;             const int row = idx >> 8, c0 = (idx & 255) * 8;
;             float r8[8];
;     ...
;             CONV1(0, bf_lo(z0[u].x), bf_lo(z1[u].x), bf_lo(z2[u].x), bf_lo(wg[u].x)) CONV1(1, bf_hi(z0[u].x), bf_hi(z1[u].x), bf_hi(z2[u].x), bf_hi(wg[u].x))
;             CONV1(2, bf_lo(z0[u].y), bf_lo(z1[u].y), bf_lo(z2[u].y), bf_lo(wg[u].y)) CONV1(3, bf_hi(z0[u].y), bf_hi(z1[u].y), bf_hi(z2[u].y), bf_hi(wg[u].y))
;             CONV1(4, bf_lo(z0[u].z), bf_lo(z1[u].z), bf_lo(z2[u].z), bf_lo(wg[u].z)) CONV1(5, bf_hi(z0[u].z), bf_hi(z1[u].z), bf_hi(z2[u].z), bf_hi(wg[u].z))
;             CONV1(6, bf_lo(z0[u].w), bf_lo(z1[u].w), bf_lo(z2[u].w), bf_lo(wg[u].w)) CONV1(7, bf_hi(z0[u].w), bf_hi(z1[u].w), bf_hi(z2[u].w), bf_hi(wg[u].w))
;     ...
;             u32x4 o; o.x = pk2(r8[0], r8[1]); o.y = pk2(r8[2], r8[3]); o.z = pk2(r8[4], r8[5]); o.w = pk2(r8[6], r8[7]);
;             *(u32x4*)(RA + (size_t)row * LDA + A_X1 + c0) = o; } } }
	v_and_b32_e32 v32, v60, v32
	v_and_b32_e32 v36, v61, v36
	v_and_b32_e32 v33, v60, v33
	v_and_b32_e32 v37, v61, v37
	v_and_b32_e32 v34, v60, v34
	v_and_b32_e32 v38, v61, v38
	v_and_b32_e32 v35, v60, v35
	v_and_b32_e32 v39, v61, v39
	v_lshlrev_b32_e32 v118, 16, v32
	v_and_b32_e32 v119, 0xffff0000, v32
	v_lshlrev_b32_e32 v120, 16, v28
	v_and_b32_e32 v121, 0xffff0000, v28
	v_lshlrev_b32_e32 v122, 16, v36
	v_and_b32_e32 v123, 0xffff0000, v36
	v_lshlrev_b32_e32 v124, 16, v40
	v_and_b32_e32 v125, 0xffff0000, v40
	v_pk_mul_f32 v[126:127], v[4:5], v[118:119]
	v_pk_fma_f32 v[126:127], v[12:13], v[120:121], v[126:127]
	v_pk_fma_f32 v[126:127], v[20:21], v[122:123], v[126:127]
	v_pk_mul_f32 v[126:127], v[124:125], v[126:127]
	v_cvt_pk_bf16_f32 v32, v126, v127
	v_lshlrev_b32_e32 v118, 16, v33
	v_and_b32_e32 v119, 0xffff0000, v33
	v_lshlrev_b32_e32 v120, 16, v29
	v_and_b32_e32 v121, 0xffff0000, v29
	v_lshlrev_b32_e32 v122, 16, v37
	v_and_b32_e32 v123, 0xffff0000, v37
	v_lshlrev_b32_e32 v124, 16, v41
	v_and_b32_e32 v125, 0xffff0000, v41
	v_pk_mul_f32 v[126:127], v[6:7], v[118:119]
	v_pk_fma_f32 v[126:127], v[14:15], v[120:121], v[126:127]
	v_pk_fma_f32 v[126:127], v[22:23], v[122:123], v[126:127]
	v_pk_mul_f32 v[126:127], v[124:125], v[126:127]
	v_cvt_pk_bf16_f32 v33, v126, v127
	v_lshlrev_b32_e32 v118, 16, v34
	v_and_b32_e32 v119, 0xffff0000, v34
	v_lshlrev_b32_e32 v120, 16, v30
	v_and_b32_e32 v121, 0xffff0000, v30
	v_lshlrev_b32_e32 v122, 16, v38
	v_and_b32_e32 v123, 0xffff0000, v38
	v_lshlrev_b32_e32 v124, 16, v42
	v_and_b32_e32 v125, 0xffff0000, v42
	v_pk_mul_f32 v[126:127], v[8:9], v[118:119]
	v_pk_fma_f32 v[126:127], v[16:17], v[120:121], v[126:127]
	v_pk_fma_f32 v[126:127], v[24:25], v[122:123], v[126:127]
	v_pk_mul_f32 v[126:127], v[124:125], v[126:127]
	v_cvt_pk_bf16_f32 v34, v126, v127
	v_lshlrev_b32_e32 v118, 16, v35
	v_and_b32_e32 v119, 0xffff0000, v35
	v_lshlrev_b32_e32 v120, 16, v31
	v_and_b32_e32 v121, 0xffff0000, v31
	v_lshlrev_b32_e32 v122, 16, v39
	v_and_b32_e32 v123, 0xffff0000, v39
	v_lshlrev_b32_e32 v124, 16, v43
	v_and_b32_e32 v125, 0xffff0000, v43
	v_pk_mul_f32 v[126:127], v[10:11], v[118:119]
	v_pk_fma_f32 v[126:127], v[18:19], v[120:121], v[126:127]
	v_pk_fma_f32 v[126:127], v[26:27], v[122:123], v[126:127]
	v_pk_mul_f32 v[126:127], v[124:125], v[126:127]
	v_cvt_pk_bf16_f32 v35, v126, v127
	global_store_dwordx4 v62, v[32:35], s[58:59]
	v_and_b32_e32 v48, v63, v48
	v_and_b32_e32 v52, v64, v52
	v_and_b32_e32 v49, v63, v49
	v_and_b32_e32 v53, v64, v53
	v_and_b32_e32 v50, v63, v50
	v_and_b32_e32 v54, v64, v54
	v_and_b32_e32 v51, v63, v51
	v_and_b32_e32 v55, v64, v55
	v_lshlrev_b32_e32 v118, 16, v48
	v_and_b32_e32 v119, 0xffff0000, v48
	v_lshlrev_b32_e32 v120, 16, v44
	v_and_b32_e32 v121, 0xffff0000, v44
	v_lshlrev_b32_e32 v122, 16, v52
	v_and_b32_e32 v123, 0xffff0000, v52
	v_lshlrev_b32_e32 v124, 16, v56
	v_and_b32_e32 v125, 0xffff0000, v56
	v_pk_mul_f32 v[126:127], v[4:5], v[118:119]
	v_pk_fma_f32 v[126:127], v[12:13], v[120:121], v[126:127]
	v_pk_fma_f32 v[126:127], v[20:21], v[122:123], v[126:127]
	v_pk_mul_f32 v[126:127], v[124:125], v[126:127]
	v_cvt_pk_bf16_f32 v48, v126, v127
	v_lshlrev_b32_e32 v118, 16, v49
	v_and_b32_e32 v119, 0xffff0000, v49
	v_lshlrev_b32_e32 v120, 16, v45
	v_and_b32_e32 v121, 0xffff0000, v45
	v_lshlrev_b32_e32 v122, 16, v53
	v_and_b32_e32 v123, 0xffff0000, v53
	v_lshlrev_b32_e32 v124, 16, v57
	v_and_b32_e32 v125, 0xffff0000, v57
	v_pk_mul_f32 v[126:127], v[6:7], v[118:119]
	v_pk_fma_f32 v[126:127], v[14:15], v[120:121], v[126:127]
	v_pk_fma_f32 v[126:127], v[22:23], v[122:123], v[126:127]
	v_pk_mul_f32 v[126:127], v[124:125], v[126:127]
	v_cvt_pk_bf16_f32 v49, v126, v127
	v_lshlrev_b32_e32 v118, 16, v50
	v_and_b32_e32 v119, 0xffff0000, v50
	v_lshlrev_b32_e32 v120, 16, v46
	v_and_b32_e32 v121, 0xffff0000, v46
	v_lshlrev_b32_e32 v122, 16, v54
	v_and_b32_e32 v123, 0xffff0000, v54
	v_lshlrev_b32_e32 v124, 16, v58
	v_and_b32_e32 v125, 0xffff0000, v58
	v_pk_mul_f32 v[126:127], v[8:9], v[118:119]
	v_pk_fma_f32 v[126:127], v[16:17], v[120:121], v[126:127]
	v_pk_fma_f32 v[126:127], v[24:25], v[122:123], v[126:127]
	v_pk_mul_f32 v[126:127], v[124:125], v[126:127]
	v_cvt_pk_bf16_f32 v50, v126, v127
	v_lshlrev_b32_e32 v118, 16, v51
	v_and_b32_e32 v119, 0xffff0000, v51
	v_lshlrev_b32_e32 v120, 16, v47
	v_and_b32_e32 v121, 0xffff0000, v47
	v_lshlrev_b32_e32 v122, 16, v55
	v_and_b32_e32 v123, 0xffff0000, v55
	v_lshlrev_b32_e32 v124, 16, v59
	v_and_b32_e32 v125, 0xffff0000, v59
	v_pk_mul_f32 v[126:127], v[10:11], v[118:119]
	v_pk_fma_f32 v[126:127], v[18:19], v[120:121], v[126:127]
	v_pk_fma_f32 v[126:127], v[26:27], v[122:123], v[126:127]
	v_pk_mul_f32 v[126:127], v[124:125], v[126:127]
	v_cvt_pk_bf16_f32 v51, v126, v127
	global_store_dwordx4 v65, v[48:51], s[58:59]
	s_sub_u32 s62, s62, 1
	s_cmp_eq_u32 s62, 0
	s_cbranch_scc1 .Lp8_lastB
; __device__ __forceinline__ unsigned pk2(float lo, float hi) { return f2bf(lo) | (f2bf(hi) << 16); }
; __global__ void __launch_bounds__(512, 2) fwd_megakernel(Args a) {
;     ...
;         for (int u = 0; u < 2; ++u) { const int idx = idx0 + u * NGT; if (idx < MT * 256) {
;             const int row = idx >> 8, c0 = (idx & 255) * 8;
;             int t, S; if (row < MP) { t = row & 2047; S = 2048; } else { t = row - MP; S = 16384; }
;             const bf16_t* zp = RB + (size_t)row * LDB + c0;
;             z1[u] = *(const u32x4*)zp;
;             const u32x4 za = *(const u32x4*)(t > 0 ? zp - LDB : zp), zb = *(const u32x4*)(t < S - 1 ? zp + LDB : zp);
;             const unsigned ma = t > 0 ? 0xffffffffu : 0u, mb = t < S - 1 ? 0xffffffffu : 0u;
;             z0[u] = (u32x4){za.x & ma, za.y & ma, za.z & ma, za.w & ma}; z2[u] = (u32x4){zb.x & mb, zb.y & mb, zb.z & mb, zb.w & mb};
;             wg[u] = *(const u32x4*)(zp + 2048);
; #pragma unroll
;             for (int k = 0; k < 3; ++k) { cw[u][k][0] = *(const f32x4*)(conv_w + k * 2048 + c0); cw[u][k][1] = *(const f32x4*)(conv_w + k * 2048 + c0 + 4); } } }
; #pragma unroll
;         for (int u = 0; u < 2; ++u) { const int idx = idx0 + u * NGT; if (idx < MT * 256) {
;             const int row = idx >> 8, c0 = (idx & 255) * 8;
;             float r8[8];
;     ...
;             CONV1(0, bf_lo(z0[u].x), bf_lo(z1[u].x), bf_lo(z2[u].x), bf_lo(wg[u].x)) CONV1(1, bf_hi(z0[u].x), bf_hi(z1[u].x), bf_hi(z2[u].x), bf_hi(wg[u].x))
;             CONV1(2, bf_lo(z0[u].y), bf_lo(z1[u].y), bf_lo(z2[u].y), bf_lo(wg[u].y)) CONV1(3, bf_hi(z0[u].y), bf_hi(z1[u].y), bf_hi(z2[u].y), bf_hi(wg[u].y))
;             CONV1(4, bf_lo(z0[u].z), bf_lo(z1[u].z), bf_lo(z2[u].z), bf_lo(wg[u].z)) CONV1(5, bf_hi(z0[u].z), bf_hi(z1[u].z), bf_hi(z2[u].z), bf_hi(wg[u].z))
;             CONV1(6, bf_lo(z0[u].w), bf_lo(z1[u].w), bf_lo(z2[u].w), bf_lo(wg[u].w)) CONV1(7, bf_hi(z0[u].w), bf_hi(z1[u].w), bf_hi(z2[u].w), bf_hi(wg[u].w))
;     ...
;             u32x4 o; o.x = pk2(r8[0], r8[1]); o.y = pk2(r8[2], r8[3]); o.z = pk2(r8[4], r8[5]); o.w = pk2(r8[6], r8[7]);
;             *(u32x4*)(RA + (size_t)row * LDA + A_X1 + c0) = o; } } }
	v_cmp_gt_u32_e32 vcc, 0x2000, v128
	v_and_b32_e32 v129, 0x7ff, v128
	v_subrev_u32_e32 v134, 0x2000, v128
	v_lshl_add_u32 v131, v128, 13, v135
	v_cndmask_b32_e32 v129, v134, v129, vcc
	v_cndmask_b32_e32 v130, v138, v137, vcc
	s_nop 0
	v_cmp_lt_u32_e32 vcc, 0, v129
	v_mul_u32_u24_e32 v134, 0x3000, v128
	v_add_u32_e32 v62, v134, v135
	v_cndmask_b32_e64 v60, 0, -1, vcc
	v_cndmask_b32_e32 v134, 0, v136, vcc
	v_sub_u32_e32 v132, v131, v134
	v_cmp_lt_u32_e32 vcc, v129, v130
	global_load_dwordx4 v[28:31], v131, s[54:55]
	global_load_dwordx4 v[32:35], v132, s[54:55]
	v_cndmask_b32_e64 v61, 0, -1, vcc
	v_cndmask_b32_e32 v134, 0, v136, vcc
	v_add_u32_e32 v133, v131, v134
	global_load_dwordx4 v[36:39], v133, s[54:55]
	global_load_dwordx4 v[40:43], v131, s[56:57]
	v_add_u32_e32 v128, s63, v128
	v_cmp_gt_u32_e32 vcc, 0x2000, v128
	v_and_b32_e32 v129, 0x7ff, v128
	v_subrev_u32_e32 v134, 0x2000, v128
	v_lshl_add_u32 v131, v128, 13, v135
	v_cndmask_b32_e32 v129, v134, v129, vcc
	v_cndmask_b32_e32 v130, v138, v137, vcc
	s_nop 0
	v_cmp_lt_u32_e32 vcc, 0, v129
	v_mul_u32_u24_e32 v134, 0x3000, v128
	v_add_u32_e32 v65, v134, v135
	v_cndmask_b32_e64 v63, 0, -1, vcc
	v_cndmask_b32_e32 v134, 0, v136, vcc
	v_sub_u32_e32 v132, v131, v134
	v_cmp_lt_u32_e32 vcc, v129, v130
	global_load_dwordx4 v[44:47], v131, s[54:55]
	global_load_dwordx4 v[48:51], v132, s[54:55]
	v_cndmask_b32_e64 v64, 0, -1, vcc
	v_cndmask_b32_e32 v134, 0, v136, vcc
	v_add_u32_e32 v133, v131, v134
	global_load_dwordx4 v[52:55], v133, s[54:55]
	global_load_dwordx4 v[56:59], v131, s[56:57]
	v_add_u32_e32 v128, s63, v128
	s_waitcnt vmcnt(8)
	v_and_b32_e32 v84, v112, v84
	v_and_b32_e32 v88, v113, v88
	v_and_b32_e32 v85, v112, v85
	v_and_b32_e32 v89, v113, v89
	v_and_b32_e32 v86, v112, v86
	v_and_b32_e32 v90, v113, v90
	v_and_b32_e32 v87, v112, v87
	v_and_b32_e32 v91, v113, v91
	v_lshlrev_b32_e32 v118, 16, v84
	v_and_b32_e32 v119, 0xffff0000, v84
	v_lshlrev_b32_e32 v120, 16, v80
	v_and_b32_e32 v121, 0xffff0000, v80
	v_lshlrev_b32_e32 v122, 16, v88
	v_and_b32_e32 v123, 0xffff0000, v88
	v_lshlrev_b32_e32 v124, 16, v92
	v_and_b32_e32 v125, 0xffff0000, v92
	v_pk_mul_f32 v[126:127], v[4:5], v[118:119]
	v_pk_fma_f32 v[126:127], v[12:13], v[120:121], v[126:127]
	v_pk_fma_f32 v[126:127], v[20:21], v[122:123], v[126:127]
	v_pk_mul_f32 v[126:127], v[124:125], v[126:127]
	v_cvt_pk_bf16_f32 v84, v126, v127
	v_lshlrev_b32_e32 v118, 16, v85
	v_and_b32_e32 v119, 0xffff0000, v85
	v_lshlrev_b32_e32 v120, 16, v81
	v_and_b32_e32 v121, 0xffff0000, v81
	v_lshlrev_b32_e32 v122, 16, v89
	v_and_b32_e32 v123, 0xffff0000, v89
	v_lshlrev_b32_e32 v124, 16, v93
	v_and_b32_e32 v125, 0xffff0000, v93
	v_pk_mul_f32 v[126:127], v[6:7], v[118:119]
	v_pk_fma_f32 v[126:127], v[14:15], v[120:121], v[126:127]
	v_pk_fma_f32 v[126:127], v[22:23], v[122:123], v[126:127]
	v_pk_mul_f32 v[126:127], v[124:125], v[126:127]
	v_cvt_pk_bf16_f32 v85, v126, v127
	v_lshlrev_b32_e32 v118, 16, v86
	v_and_b32_e32 v119, 0xffff0000, v86
	v_lshlrev_b32_e32 v120, 16, v82
	v_and_b32_e32 v121, 0xffff0000, v82
	v_lshlrev_b32_e32 v122, 16, v90
	v_and_b32_e32 v123, 0xffff0000, v90
	v_lshlrev_b32_e32 v124, 16, v94
	v_and_b32_e32 v125, 0xffff0000, v94
	v_pk_mul_f32 v[126:127], v[8:9], v[118:119]
	v_pk_fma_f32 v[126:127], v[16:17], v[120:121], v[126:127]
	v_pk_fma_f32 v[126:127], v[24:25], v[122:123], v[126:127]
	v_pk_mul_f32 v[126:127], v[124:125], v[126:127]
	v_cvt_pk_bf16_f32 v86, v126, v127
	v_lshlrev_b32_e32 v118, 16, v87
	v_and_b32_e32 v119, 0xffff0000, v87
	v_lshlrev_b32_e32 v120, 16, v83
	v_and_b32_e32 v121, 0xffff0000, v83
	v_lshlrev_b32_e32 v122, 16, v91
	v_and_b32_e32 v123, 0xffff0000, v91
	v_lshlrev_b32_e32 v124, 16, v95
	v_and_b32_e32 v125, 0xffff0000, v95
	v_pk_mul_f32 v[126:127], v[10:11], v[118:119]
	v_pk_fma_f32 v[126:127], v[18:19], v[120:121], v[126:127]
	v_pk_fma_f32 v[126:127], v[26:27], v[122:123], v[126:127]
	v_pk_mul_f32 v[126:127], v[124:125], v[126:127]
	v_cvt_pk_bf16_f32 v87, v126, v127
	global_store_dwordx4 v114, v[84:87], s[58:59]
	v_and_b32_e32 v100, v115, v100
	v_and_b32_e32 v104, v116, v104
	v_and_b32_e32 v101, v115, v101
	v_and_b32_e32 v105, v116, v105
	v_and_b32_e32 v102, v115, v102
	v_and_b32_e32 v106, v116, v106
	v_and_b32_e32 v103, v115, v103
	v_and_b32_e32 v107, v116, v107
	v_lshlrev_b32_e32 v118, 16, v100
	v_and_b32_e32 v119, 0xffff0000, v100
	v_lshlrev_b32_e32 v120, 16, v96
	v_and_b32_e32 v121, 0xffff0000, v96
	v_lshlrev_b32_e32 v122, 16, v104
	v_and_b32_e32 v123, 0xffff0000, v104
	v_lshlrev_b32_e32 v124, 16, v108
	v_and_b32_e32 v125, 0xffff0000, v108
	v_pk_mul_f32 v[126:127], v[4:5], v[118:119]
	v_pk_fma_f32 v[126:127], v[12:13], v[120:121], v[126:127]
	v_pk_fma_f32 v[126:127], v[20:21], v[122:123], v[126:127]
	v_pk_mul_f32 v[126:127], v[124:125], v[126:127]
	v_cvt_pk_bf16_f32 v100, v126, v127
	v_lshlrev_b32_e32 v118, 16, v101
	v_and_b32_e32 v119, 0xffff0000, v101
	v_lshlrev_b32_e32 v120, 16, v97
	v_and_b32_e32 v121, 0xffff0000, v97
	v_lshlrev_b32_e32 v122, 16, v105
	v_and_b32_e32 v123, 0xffff0000, v105
	v_lshlrev_b32_e32 v124, 16, v109
	v_and_b32_e32 v125, 0xffff0000, v109
	v_pk_mul_f32 v[126:127], v[6:7], v[118:119]
	v_pk_fma_f32 v[126:127], v[14:15], v[120:121], v[126:127]
	v_pk_fma_f32 v[126:127], v[22:23], v[122:123], v[126:127]
	v_pk_mul_f32 v[126:127], v[124:125], v[126:127]
	v_cvt_pk_bf16_f32 v101, v126, v127
	v_lshlrev_b32_e32 v118, 16, v102
	v_and_b32_e32 v119, 0xffff0000, v102
	v_lshlrev_b32_e32 v120, 16, v98
	v_and_b32_e32 v121, 0xffff0000, v98
	v_lshlrev_b32_e32 v122, 16, v106
	v_and_b32_e32 v123, 0xffff0000, v106
	v_lshlrev_b32_e32 v124, 16, v110
	v_and_b32_e32 v125, 0xffff0000, v110
	v_pk_mul_f32 v[126:127], v[8:9], v[118:119]
	v_pk_fma_f32 v[126:127], v[16:17], v[120:121], v[126:127]
	v_pk_fma_f32 v[126:127], v[24:25], v[122:123], v[126:127]
	v_pk_mul_f32 v[126:127], v[124:125], v[126:127]
	v_cvt_pk_bf16_f32 v102, v126, v127
	v_lshlrev_b32_e32 v118, 16, v103
	v_and_b32_e32 v119, 0xffff0000, v103
	v_lshlrev_b32_e32 v120, 16, v99
	v_and_b32_e32 v121, 0xffff0000, v99
	v_lshlrev_b32_e32 v122, 16, v107
	v_and_b32_e32 v123, 0xffff0000, v107
	v_lshlrev_b32_e32 v124, 16, v111
	v_and_b32_e32 v125, 0xffff0000, v111
	v_pk_mul_f32 v[126:127], v[10:11], v[118:119]
	v_pk_fma_f32 v[126:127], v[18:19], v[120:121], v[126:127]
	v_pk_fma_f32 v[126:127], v[26:27], v[122:123], v[126:127]
	v_pk_mul_f32 v[126:127], v[124:125], v[126:127]
	v_cvt_pk_bf16_f32 v103, v126, v127
	global_store_dwordx4 v117, v[100:103], s[58:59]
	s_sub_u32 s62, s62, 1
	s_branch .Lp8_loop
; __device__ __forceinline__ unsigned pk2(float lo, float hi) { return f2bf(lo) | (f2bf(hi) << 16); }
; __global__ void __launch_bounds__(512, 2) fwd_megakernel(Args a) {
;     ...
;         for (int u = 0; u < 2; ++u) { const int idx = idx0 + u * NGT; if (idx < MT * 256) {
;             const int row = idx >> 8, c0 = (idx & 255) * 8;
;             float r8[8];
;     ...
;             CONV1(0, bf_lo(z0[u].x), bf_lo(z1[u].x), bf_lo(z2[u].x), bf_lo(wg[u].x)) CONV1(1, bf_hi(z0[u].x), bf_hi(z1[u].x), bf_hi(z2[u].x), bf_hi(wg[u].x))
;             CONV1(2, bf_lo(z0[u].y), bf_lo(z1[u].y), bf_lo(z2[u].y), bf_lo(wg[u].y)) CONV1(3, bf_hi(z0[u].y), bf_hi(z1[u].y), bf_hi(z2[u].y), bf_hi(wg[u].y))
;             CONV1(4, bf_lo(z0[u].z), bf_lo(z1[u].z), bf_lo(z2[u].z), bf_lo(wg[u].z)) CONV1(5, bf_hi(z0[u].z), bf_hi(z1[u].z), bf_hi(z2[u].z), bf_hi(wg[u].z))
;             CONV1(6, bf_lo(z0[u].w), bf_lo(z1[u].w), bf_lo(z2[u].w), bf_lo(wg[u].w)) CONV1(7, bf_hi(z0[u].w), bf_hi(z1[u].w), bf_hi(z2[u].w), bf_hi(wg[u].w))
;     ...
;             u32x4 o; o.x = pk2(r8[0], r8[1]); o.y = pk2(r8[2], r8[3]); o.z = pk2(r8[4], r8[5]); o.w = pk2(r8[6], r8[7]);
;             *(u32x4*)(RA + (size_t)row * LDA + A_X1 + c0) = o; } } }
.Lp8_lastB:
	s_waitcnt vmcnt(0)
	v_and_b32_e32 v84, v112, v84
	v_and_b32_e32 v88, v113, v88
	v_and_b32_e32 v85, v112, v85
	v_and_b32_e32 v89, v113, v89
	v_and_b32_e32 v86, v112, v86
	v_and_b32_e32 v90, v113, v90
	v_and_b32_e32 v87, v112, v87
	v_and_b32_e32 v91, v113, v91
	v_lshlrev_b32_e32 v118, 16, v84
	v_and_b32_e32 v119, 0xffff0000, v84
	v_lshlrev_b32_e32 v120, 16, v80
	v_and_b32_e32 v121, 0xffff0000, v80
	v_lshlrev_b32_e32 v122, 16, v88
	v_and_b32_e32 v123, 0xffff0000, v88
	v_lshlrev_b32_e32 v124, 16, v92
	v_and_b32_e32 v125, 0xffff0000, v92
	v_pk_mul_f32 v[126:127], v[4:5], v[118:119]
	v_pk_fma_f32 v[126:127], v[12:13], v[120:121], v[126:127]
	v_pk_fma_f32 v[126:127], v[20:21], v[122:123], v[126:127]
	v_pk_mul_f32 v[126:127], v[124:125], v[126:127]
	v_cvt_pk_bf16_f32 v84, v126, v127
	v_lshlrev_b32_e32 v118, 16, v85
	v_and_b32_e32 v119, 0xffff0000, v85
	v_lshlrev_b32_e32 v120, 16, v81
	v_and_b32_e32 v121, 0xffff0000, v81
	v_lshlrev_b32_e32 v122, 16, v89
	v_and_b32_e32 v123, 0xffff0000, v89
	v_lshlrev_b32_e32 v124, 16, v93
	v_and_b32_e32 v125, 0xffff0000, v93
	v_pk_mul_f32 v[126:127], v[6:7], v[118:119]
	v_pk_fma_f32 v[126:127], v[14:15], v[120:121], v[126:127]
	v_pk_fma_f32 v[126:127], v[22:23], v[122:123], v[126:127]
	v_pk_mul_f32 v[126:127], v[124:125], v[126:127]
	v_cvt_pk_bf16_f32 v85, v126, v127
	v_lshlrev_b32_e32 v118, 16, v86
	v_and_b32_e32 v119, 0xffff0000, v86
	v_lshlrev_b32_e32 v120, 16, v82
	v_and_b32_e32 v121, 0xffff0000, v82
	v_lshlrev_b32_e32 v122, 16, v90
	v_and_b32_e32 v123, 0xffff0000, v90
	v_lshlrev_b32_e32 v124, 16, v94
	v_and_b32_e32 v125, 0xffff0000, v94
	v_pk_mul_f32 v[126:127], v[8:9], v[118:119]
	v_pk_fma_f32 v[126:127], v[16:17], v[120:121], v[126:127]
	v_pk_fma_f32 v[126:127], v[24:25], v[122:123], v[126:127]
	v_pk_mul_f32 v[126:127], v[124:125], v[126:127]
	v_cvt_pk_bf16_f32 v86, v126, v127
	v_lshlrev_b32_e32 v118, 16, v87
	v_and_b32_e32 v119, 0xffff0000, v87
	v_lshlrev_b32_e32 v120, 16, v83
	v_and_b32_e32 v121, 0xffff0000, v83
	v_lshlrev_b32_e32 v122, 16, v91
	v_and_b32_e32 v123, 0xffff0000, v91
	v_lshlrev_b32_e32 v124, 16, v95
	v_and_b32_e32 v125, 0xffff0000, v95
	v_pk_mul_f32 v[126:127], v[10:11], v[118:119]
	v_pk_fma_f32 v[126:127], v[18:19], v[120:121], v[126:127]
	v_pk_fma_f32 v[126:127], v[26:27], v[122:123], v[126:127]
	v_pk_mul_f32 v[126:127], v[124:125], v[126:127]
	v_cvt_pk_bf16_f32 v87, v126, v127
	global_store_dwordx4 v114, v[84:87], s[58:59]
	v_and_b32_e32 v100, v115, v100
	v_and_b32_e32 v104, v116, v104
	v_and_b32_e32 v101, v115, v101
	v_and_b32_e32 v105, v116, v105
	v_and_b32_e32 v102, v115, v102
	v_and_b32_e32 v106, v116, v106
	v_and_b32_e32 v103, v115, v103
	v_and_b32_e32 v107, v116, v107
	v_lshlrev_b32_e32 v118, 16, v100
	v_and_b32_e32 v119, 0xffff0000, v100
	v_lshlrev_b32_e32 v120, 16, v96
	v_and_b32_e32 v121, 0xffff0000, v96
	v_lshlrev_b32_e32 v122, 16, v104
	v_and_b32_e32 v123, 0xffff0000, v104
	v_lshlrev_b32_e32 v124, 16, v108
	v_and_b32_e32 v125, 0xffff0000, v108
	v_pk_mul_f32 v[126:127], v[4:5], v[118:119]
	v_pk_fma_f32 v[126:127], v[12:13], v[120:121], v[126:127]
	v_pk_fma_f32 v[126:127], v[20:21], v[122:123], v[126:127]
	v_pk_mul_f32 v[126:127], v[124:125], v[126:127]
	v_cvt_pk_bf16_f32 v100, v126, v127
	v_lshlrev_b32_e32 v118, 16, v101
	v_and_b32_e32 v119, 0xffff0000, v101
	v_lshlrev_b32_e32 v120, 16, v97
	v_and_b32_e32 v121, 0xffff0000, v97
	v_lshlrev_b32_e32 v122, 16, v105
	v_and_b32_e32 v123, 0xffff0000, v105
	v_lshlrev_b32_e32 v124, 16, v109
	v_and_b32_e32 v125, 0xffff0000, v109
	v_pk_mul_f32 v[126:127], v[6:7], v[118:119]
	v_pk_fma_f32 v[126:127], v[14:15], v[120:121], v[126:127]
	v_pk_fma_f32 v[126:127], v[22:23], v[122:123], v[126:127]
	v_pk_mul_f32 v[126:127], v[124:125], v[126:127]
	v_cvt_pk_bf16_f32 v101, v126, v127
	v_lshlrev_b32_e32 v118, 16, v102
	v_and_b32_e32 v119, 0xffff0000, v102
	v_lshlrev_b32_e32 v120, 16, v98
	v_and_b32_e32 v121, 0xffff0000, v98
	v_lshlrev_b32_e32 v122, 16, v106
	v_and_b32_e32 v123, 0xffff0000, v106
	v_lshlrev_b32_e32 v124, 16, v110
	v_and_b32_e32 v125, 0xffff0000, v110
	v_pk_mul_f32 v[126:127], v[8:9], v[118:119]
	v_pk_fma_f32 v[126:127], v[16:17], v[120:121], v[126:127]
	v_pk_fma_f32 v[126:127], v[24:25], v[122:123], v[126:127]
	v_pk_mul_f32 v[126:127], v[124:125], v[126:127]
	v_cvt_pk_bf16_f32 v102, v126, v127
	v_lshlrev_b32_e32 v118, 16, v103
	v_and_b32_e32 v119, 0xffff0000, v103
	v_lshlrev_b32_e32 v120, 16, v99
	v_and_b32_e32 v121, 0xffff0000, v99
	v_lshlrev_b32_e32 v122, 16, v107
	v_and_b32_e32 v123, 0xffff0000, v107
	v_lshlrev_b32_e32 v124, 16, v111
	v_and_b32_e32 v125, 0xffff0000, v111
	v_pk_mul_f32 v[126:127], v[10:11], v[118:119]
	v_pk_fma_f32 v[126:127], v[18:19], v[120:121], v[126:127]
	v_pk_fma_f32 v[126:127], v[26:27], v[122:123], v[126:127]
	v_pk_mul_f32 v[126:127], v[124:125], v[126:127]
	v_cvt_pk_bf16_f32 v103, v126, v127
	global_store_dwordx4 v117, v[100:103], s[58:59]
	s_branch .LBB0_925
.Lp8_old:
	s_cbranch_execz .LBB0_925
	v_mov_b32_e32 v5, 0
	v_mov_b32_e32 v6, v5
	v_mov_b32_e32 v7, v5
	v_mov_b32_e32 v4, v5
	v_mov_b64_e32 v[16:17], v[6:7]
	v_mov_b64_e32 v[12:13], v[2:3]
	v_mov_b64_e32 v[10:11], v[0:1]
	v_readlane_b32 s0, v255, 9
	v_mov_b64_e32 v[14:15], v[4:5]
	v_mov_b64_e32 v[12:13], v[6:7]
	s_lshl_b32 s23, s0, 10
	s_lshl_b32 s24, s0, 13
	s_mov_b64 s[16:17], 0
	s_movk_i32 s25, 0x2000
	v_mov_b32_e32 v86, 0x3fff
	v_mov_b32_e32 v87, 0x7ff
	v_mov_b32_e32 v88, 0xffffe000
	v_mov_b32_e32 v89, 0x2000
	s_movk_i32 s26, 0x1000
	s_mov_b64 s[18:19], 0x2000
	s_mov_b64 s[20:21], 0x4000
	s_movk_i32 s27, 0x4000
	s_mov_b32 s28, 0xffff0000
	s_movk_i32 s29, 0x7fff
	s_mov_b32 s30, 0x5fffff
	v_mov_b64_e32 v[10:11], v[4:5]
	v_mov_b32_e32 v18, v5
	v_mov_b32_e32 v19, v5
	v_mov_b32_e32 v20, v5
	v_mov_b32_e32 v21, v5
	v_mov_b32_e32 v22, v5
	v_mov_b32_e32 v23, v5
	v_mov_b32_e32 v24, v5
	v_mov_b32_e32 v25, v5
	v_readlane_b32 s1, v255, 10
	v_mov_b64_e32 v[8:9], v[2:3]
	v_mov_b64_e32 v[6:7], v[0:1]
	s_branch .LBB0_921
